# prepass A rewritten (gains in registers, 3 rows in flight), scan loads batched, final pass batched, rowsum tree, redundant max removed
# speedup vs baseline: 1.0203x; 1.0203x over previous
.LBB0_265:
	v_pk_add_f32 v[50:51], v[50:51], v[144:145]
	v_pk_add_f32 v[52:53], v[52:53], v[36:37]
	v_pk_add_f32 v[54:55], v[54:55], v[38:39]
	v_pk_add_f32 v[56:57], v[56:57], v[40:41]
	v_pk_add_f32 v[58:59], v[58:59], v[42:43]
	v_pk_add_f32 v[60:61], v[60:61], v[44:45]
	v_pk_add_f32 v[62:63], v[62:63], v[46:47]
	v_add_f32_e32 v32, v48, v112
	v_add_f32_e32 v33, v49, v125
	v_pk_add_f32 v[50:51], v[50:51], v[52:53]
	v_pk_add_f32 v[54:55], v[54:55], v[56:57]
	v_pk_add_f32 v[58:59], v[58:59], v[60:61]
	v_add_f32_e32 v32, v32, v33
	v_pk_add_f32 v[50:51], v[50:51], v[54:55]
	v_pk_add_f32 v[58:59], v[58:59], v[62:63]
	v_pk_add_f32 v[50:51], v[50:51], v[58:59]
	v_add_f32_e32 v32, v32, v50
	v_add_f32_e32 v32, v32, v51
	s_add_i32 s18, s18, 1
	v_add_f32_e32 v136, v136, v32
	v_add_u32_e32 v143, 64, v143
	s_cmp_ge_i32 s18, s3
	v_add_u32_e32 v124, 64, v124
	s_waitcnt lgkmcnt(0)
	s_barrier
	s_cbranch_scc1 .LBB0_274

.LBB0_268:
	s_add_i32 s0, s2, s18
	s_and_b32 s4, s0, 1
	s_mul_i32 s0, s4, 0x5100
	s_addk_i32 s0, 0x100
	v_lshl_add_u32 v60, v133, 2, s0
	v_add3_u32 v97, s0, v139, v140
	ds_read_b128 v[32:35], v60 offset:20480
	ds_read_b128 v[36:39], v60 offset:20512
	ds_read_b128 v[40:43], v60 offset:20544
	ds_read_b128 v[44:47], v60 offset:20576
	ds_read_b128 v[48:51], v60 offset:20608
	ds_read_b128 v[52:55], v60 offset:20640
	ds_read_b128 v[56:59], v60 offset:20672
	ds_read_b128 v[60:63], v60 offset:20704
	ds_read_b128 v[88:91], v97
	ds_read_b128 v[92:95], v97 offset:512
	v_sub_f32_e32 v96, v130, v135
	s_waitcnt lgkmcnt(6)
	v_sub_f32_e32 v47, v96, v47
	v_sub_f32_e32 v46, v96, v46
	v_sub_f32_e32 v45, v96, v45
	v_sub_f32_e32 v44, v96, v44
	v_sub_f32_e32 v43, v96, v43
	v_sub_f32_e32 v42, v96, v42
	v_sub_f32_e32 v41, v96, v41
	v_sub_f32_e32 v40, v96, v40
	v_sub_f32_e32 v39, v96, v39
	v_sub_f32_e32 v38, v96, v38
	v_sub_f32_e32 v37, v96, v37
	v_sub_f32_e32 v36, v96, v36
	v_sub_f32_e32 v35, v96, v35
	v_sub_f32_e32 v34, v96, v34
	v_sub_f32_e32 v33, v96, v33
	v_sub_f32_e32 v32, v96, v32
	s_waitcnt lgkmcnt(2)
	v_sub_f32_e32 v63, v96, v63
	v_sub_f32_e32 v62, v96, v62
	v_sub_f32_e32 v61, v96, v61
	v_sub_f32_e32 v60, v96, v60
	v_sub_f32_e32 v59, v96, v59
	v_sub_f32_e32 v58, v96, v58
	v_sub_f32_e32 v57, v96, v57
	v_sub_f32_e32 v56, v96, v56
	v_sub_f32_e32 v55, v96, v55
	v_sub_f32_e32 v54, v96, v54
	v_sub_f32_e32 v53, v96, v53
	v_sub_f32_e32 v52, v96, v52
	v_sub_f32_e32 v51, v96, v51
	v_sub_f32_e32 v50, v96, v50
	v_sub_f32_e32 v49, v96, v49
	v_sub_f32_e32 v48, v96, v48
	s_waitcnt lgkmcnt(1)
	v_mfma_f32_32x32x16_bf16 v[32:47], v[88:91], v[64:67], v[32:47]
	v_add_u32_e32 v112, s0, v134
	s_waitcnt lgkmcnt(0)
	v_mfma_f32_32x32x16_bf16 v[48:63], v[92:95], v[64:67], v[48:63]
	ds_read_b128 v[88:91], v97 offset:2048
	ds_read_b128 v[92:95], v97 offset:2560
	s_waitcnt lgkmcnt(1)
	v_mfma_f32_32x32x16_bf16 v[32:47], v[88:91], v[68:71], v[32:47]
	s_waitcnt lgkmcnt(0)
	v_mfma_f32_32x32x16_bf16 v[48:63], v[92:95], v[68:71], v[48:63]
	ds_read_b128 v[88:91], v97 offset:4096
	ds_read_b128 v[92:95], v97 offset:4608
	s_waitcnt lgkmcnt(1)
	v_mfma_f32_32x32x16_bf16 v[32:47], v[88:91], v[72:75], v[32:47]
	s_waitcnt lgkmcnt(0)
	v_mfma_f32_32x32x16_bf16 v[48:63], v[92:95], v[72:75], v[48:63]
	ds_read_b128 v[92:95], v97 offset:6144
	ds_read_b64_tr_b16 v[118:119], v112 offset:12288
	ds_read_b64_tr_b16 v[120:121], v112 offset:12800
	ds_read_b64_tr_b16 v[108:109], v112 offset:13312
	ds_read_b64_tr_b16 v[110:111], v112 offset:13824
	ds_read_b64_tr_b16 v[100:101], v112 offset:14336
	ds_read_b64_tr_b16 v[102:103], v112 offset:14848
	ds_read_b64_tr_b16 v[88:89], v112 offset:15360
	ds_read_b64_tr_b16 v[90:91], v112 offset:15872
	ds_read_b128 v[144:147], v97 offset:6656
	s_waitcnt lgkmcnt(9)
	v_mfma_f32_32x32x16_bf16 v[32:47], v[92:95], v[76:79], v[32:47]
	ds_read_b64_tr_b16 v[114:115], v112 offset:16384
	ds_read_b64_tr_b16 v[116:117], v112 offset:16896
	ds_read_b64_tr_b16 v[104:105], v112 offset:17408
	ds_read_b64_tr_b16 v[106:107], v112 offset:17920
	ds_read_b64_tr_b16 v[96:97], v112 offset:18432
	ds_read_b64_tr_b16 v[98:99], v112 offset:18944
	ds_read_b64_tr_b16 v[92:93], v112 offset:19456
	ds_read_b64_tr_b16 v[94:95], v112 offset:19968
	s_waitcnt lgkmcnt(8)
	v_mfma_f32_32x32x16_bf16 v[48:63], v[144:147], v[76:79], v[48:63]
	v_max3_f32 v112, v32, v33, v48
	v_max3_f32 v125, v34, v35, v49
	v_max3_f32 v112, v112, v50, v51
	v_max3_f32 v125, v125, v38, v39
	v_max3_f32 v112, v112, v36, v37
	v_max3_f32 v125, v125, v54, v55
	v_max3_f32 v112, v112, v52, v53
	v_max3_f32 v125, v125, v42, v43
	v_max3_f32 v112, v112, v40, v41
	v_max3_f32 v125, v125, v58, v59
	v_max3_f32 v112, v112, v56, v57
	v_max3_f32 v125, v125, v46, v47
	v_max3_f32 v112, v112, v44, v45
	v_max3_f32 v125, v125, v62, v63
	v_max3_f32 v112, v112, v60, v61
	v_max_f32_e32 v112, v112, v125
	v_mov_b32_e32 v125, v112
	s_nop 1
	v_permlane32_swap_b32_e32 v112, v125
	v_max_f32_e32 v112, v112, v125
	v_cmp_lt_f32_e32 vcc, s75, v112
	s_cbranch_vccz .LBB0_272
	v_max_f32_e32 v112, v112, v112
	v_max_f32_e32 v112, 0, v112
	v_exp_f32_e64 v125, -v112
	s_and_saveexec_b64 s[0:1], s[40:41]
	ds_write_b32 v138, v125 offset:41472
	s_or_b64 exec, exec, s[0:1]
	s_waitcnt lgkmcnt(0)
	ds_read_b128 v[144:147], v137 offset:41472
	ds_read_b128 v[148:151], v137 offset:41504
	ds_read_b128 v[152:155], v137 offset:41536
	ds_read_b128 v[192:195], v137 offset:41568
	s_waitcnt lgkmcnt(0)
	v_add_f32_e32 v135, v135, v112
	v_pk_add_f32 v[32:33], v[32:33], v[112:113] op_sel_hi:[1,0] neg_lo:[0,1] neg_hi:[0,1]
	v_pk_add_f32 v[48:49], v[48:49], v[112:113] op_sel_hi:[1,0] neg_lo:[0,1] neg_hi:[0,1]
	v_pk_add_f32 v[34:35], v[34:35], v[112:113] op_sel_hi:[1,0] neg_lo:[0,1] neg_hi:[0,1]
	v_pk_add_f32 v[50:51], v[50:51], v[112:113] op_sel_hi:[1,0] neg_lo:[0,1] neg_hi:[0,1]
	v_pk_add_f32 v[36:37], v[36:37], v[112:113] op_sel_hi:[1,0] neg_lo:[0,1] neg_hi:[0,1]
	v_pk_add_f32 v[52:53], v[52:53], v[112:113] op_sel_hi:[1,0] neg_lo:[0,1] neg_hi:[0,1]
	v_pk_add_f32 v[38:39], v[38:39], v[112:113] op_sel_hi:[1,0] neg_lo:[0,1] neg_hi:[0,1]
	v_pk_add_f32 v[54:55], v[54:55], v[112:113] op_sel_hi:[1,0] neg_lo:[0,1] neg_hi:[0,1]
	v_pk_add_f32 v[40:41], v[40:41], v[112:113] op_sel_hi:[1,0] neg_lo:[0,1] neg_hi:[0,1]
	v_pk_add_f32 v[56:57], v[56:57], v[112:113] op_sel_hi:[1,0] neg_lo:[0,1] neg_hi:[0,1]
	v_pk_add_f32 v[42:43], v[42:43], v[112:113] op_sel_hi:[1,0] neg_lo:[0,1] neg_hi:[0,1]
	v_pk_add_f32 v[58:59], v[58:59], v[112:113] op_sel_hi:[1,0] neg_lo:[0,1] neg_hi:[0,1]
	v_pk_add_f32 v[44:45], v[44:45], v[112:113] op_sel_hi:[1,0] neg_lo:[0,1] neg_hi:[0,1]
	v_pk_add_f32 v[60:61], v[60:61], v[112:113] op_sel_hi:[1,0] neg_lo:[0,1] neg_hi:[0,1]
	v_pk_add_f32 v[46:47], v[46:47], v[112:113] op_sel_hi:[1,0] neg_lo:[0,1] neg_hi:[0,1]
	v_pk_add_f32 v[62:63], v[62:63], v[112:113] op_sel_hi:[1,0] neg_lo:[0,1] neg_hi:[0,1]
	v_mul_f32_e32 v136, v136, v125
	s_waitcnt lgkmcnt(0)
	v_pk_mul_f32 v[14:15], v[14:15], v[194:195]
	v_pk_mul_f32 v[10:11], v[10:11], v[154:155]
	v_pk_mul_f32 v[6:7], v[6:7], v[150:151]
	v_pk_mul_f32 v[2:3], v[2:3], v[146:147]
	v_pk_mul_f32 v[12:13], v[12:13], v[192:193]
	v_pk_mul_f32 v[8:9], v[8:9], v[152:153]
	v_pk_mul_f32 v[4:5], v[4:5], v[148:149]
	v_pk_mul_f32 v[0:1], v[0:1], v[144:145]
	v_pk_mul_f32 v[30:31], v[30:31], v[194:195]
	v_pk_mul_f32 v[26:27], v[26:27], v[154:155]
	v_pk_mul_f32 v[22:23], v[22:23], v[150:151]
	v_pk_mul_f32 v[18:19], v[18:19], v[146:147]
	v_pk_mul_f32 v[28:29], v[28:29], v[192:193]
	v_pk_mul_f32 v[24:25], v[24:25], v[152:153]
	v_pk_mul_f32 v[20:21], v[20:21], v[148:149]
	v_pk_mul_f32 v[16:17], v[16:17], v[144:145]

.LBB0_349:
	v_pk_add_f32 v[66:67], v[66:67], v[200:201]
	v_pk_add_f32 v[68:69], v[68:69], v[6:7]
	v_pk_add_f32 v[70:71], v[70:71], v[8:9]
	v_pk_add_f32 v[72:73], v[72:73], v[10:11]
	v_pk_add_f32 v[74:75], v[74:75], v[12:13]
	v_pk_add_f32 v[76:77], v[76:77], v[14:15]
	v_pk_add_f32 v[78:79], v[78:79], v[16:17]
	v_add_f32_e32 v3, v64, v115
	v_add_f32_e32 v4, v65, v171
	v_pk_add_f32 v[66:67], v[66:67], v[68:69]
	v_pk_add_f32 v[70:71], v[70:71], v[72:73]
	v_pk_add_f32 v[74:75], v[74:75], v[76:77]
	v_add_f32_e32 v3, v3, v4
	v_pk_add_f32 v[66:67], v[66:67], v[70:71]
	v_pk_add_f32 v[74:75], v[74:75], v[78:79]
	v_pk_add_f32 v[66:67], v[66:67], v[74:75]
	v_add_f32_e32 v3, v3, v66
	v_add_f32_e32 v3, v3, v67
	s_add_i32 s2, s2, 1
	v_add_f32_e32 v163, v163, v3
	v_add_u32_e32 v114, 64, v114
	s_cmp_eq_u32 s22, s2
	v_add_u32_e32 v170, 64, v170
	s_waitcnt vmcnt(0)
	ds_write_b128 v2, v[148:151] offset:12288
	s_waitcnt lgkmcnt(0)
	s_barrier
	s_cbranch_scc1 .LBB0_358

.LBB0_352:
	s_add_i32 s0, s2, -1
	s_and_b32 s3, s0, 1
	s_xor_b32 s0, s3, 1
	s_mulk_i32 s0, 0x5100
	v_add_u32_e32 v84, s0, v197
	ds_read_b128 v[18:21], v84
	ds_read_b128 v[22:25], v84 offset:512
	v_ashrrev_i32_e32 v115, 31, v114
	s_waitcnt lgkmcnt(1)
	v_mfma_f32_32x32x16_bf16 v[2:17], v[18:21], v[116:119], v[96:111]
	s_waitcnt lgkmcnt(0)
	v_mfma_f32_32x32x16_bf16 v[64:79], v[22:25], v[116:119], v[96:111]
	ds_read_b128 v[18:21], v84 offset:2048
	ds_read_b128 v[22:25], v84 offset:2560
	s_waitcnt lgkmcnt(0)
	v_mfma_f32_32x32x16_bf16 v[64:79], v[22:25], v[120:123], v[64:79]
	v_mfma_f32_32x32x16_bf16 v[2:17], v[18:21], v[120:123], v[2:17]
	ds_read_b128 v[18:21], v84 offset:4096
	ds_read_b128 v[22:25], v84 offset:4608
	s_waitcnt lgkmcnt(0)
	v_mfma_f32_32x32x16_bf16 v[64:79], v[22:25], v[124:127], v[64:79]
	v_mfma_f32_32x32x16_bf16 v[2:17], v[18:21], v[124:127], v[2:17]
	ds_read_b128 v[18:21], v84 offset:6144
	ds_read_b128 v[22:25], v84 offset:6656
	s_waitcnt lgkmcnt(0)
	v_mfma_f32_32x32x16_bf16 v[64:79], v[22:25], v[128:131], v[64:79]
	v_lshlrev_b64 v[22:23], 11, v[114:115]
	v_lshl_add_u64 v[26:27], v[30:31], 0, v[22:23]
	global_load_dwordx4 v[148:151], v[26:27], off offset:128
	ds_read_b128 v[22:25], v84 offset:8704
	ds_read_b128 v[26:29], v84 offset:10240
	v_add_u32_e32 v115, s0, v196
	v_mfma_f32_32x32x16_bf16 v[2:17], v[18:21], v[128:131], v[2:17]
	ds_read_b128 v[18:21], v84 offset:8192
	s_waitcnt lgkmcnt(0)
	v_mfma_f32_32x32x16_bf16 v[2:17], v[18:21], v[132:135], v[2:17]
	ds_read_b64_tr_b16 v[152:153], v115 offset:12288
	ds_read_b64_tr_b16 v[154:155], v115 offset:12800
	ds_read_b64_tr_b16 v[88:89], v115 offset:13312
	ds_read_b64_tr_b16 v[90:91], v115 offset:13824
	ds_read_b64_tr_b16 v[80:81], v115 offset:14336
	ds_read_b64_tr_b16 v[82:83], v115 offset:14848
	ds_read_b64_tr_b16 v[18:19], v115 offset:15360
	ds_read_b64_tr_b16 v[20:21], v115 offset:15872
	ds_read_b128 v[200:203], v84 offset:10752
	v_mfma_f32_32x32x16_bf16 v[64:79], v[22:25], v[132:135], v[64:79]
	v_mfma_f32_32x32x16_bf16 v[2:17], v[26:29], v[136:139], v[2:17]
	ds_read_b64_tr_b16 v[92:93], v115 offset:16384
	ds_read_b64_tr_b16 v[94:95], v115 offset:16896
	ds_read_b64_tr_b16 v[84:85], v115 offset:17408
	ds_read_b64_tr_b16 v[86:87], v115 offset:17920
	ds_read_b64_tr_b16 v[26:27], v115 offset:18432
	ds_read_b64_tr_b16 v[28:29], v115 offset:18944
	ds_read_b64_tr_b16 v[22:23], v115 offset:19456
	ds_read_b64_tr_b16 v[24:25], v115 offset:19968
	s_waitcnt lgkmcnt(8)
	v_mfma_f32_32x32x16_bf16 v[64:79], v[200:203], v[136:139], v[64:79]
	v_max3_f32 v115, v2, v3, v64
	v_max3_f32 v171, v4, v5, v65
	v_max3_f32 v115, v115, v66, v67
	v_max3_f32 v171, v171, v8, v9
	v_max3_f32 v115, v115, v6, v7
	v_max3_f32 v171, v171, v70, v71
	v_max3_f32 v115, v115, v68, v69
	v_max3_f32 v171, v171, v12, v13
	v_max3_f32 v115, v115, v10, v11
	v_max3_f32 v171, v171, v74, v75
	v_max3_f32 v115, v115, v72, v73
	v_max3_f32 v171, v171, v16, v17
	v_max3_f32 v115, v115, v14, v15
	v_max3_f32 v171, v171, v78, v79
	v_max3_f32 v115, v115, v76, v77
	v_max_f32_e32 v115, v115, v171
	v_mov_b32_e32 v171, v115
	s_nop 1
	v_permlane32_swap_b32_e32 v115, v171
	v_max_f32_e32 v115, v115, v171
	v_cmp_lt_f32_e32 vcc, s75, v115
	s_cbranch_vccz .LBB0_356
	v_max_f32_e32 v96, v115, v115
	v_max_f32_e32 v98, 0, v96
	v_exp_f32_e64 v115, -v98
	s_and_saveexec_b64 s[0:1], s[40:41]
	ds_write_b32 v198, v115 offset:41472
	s_or_b64 exec, exec, s[0:1]
	s_waitcnt lgkmcnt(0)
	ds_read_b128 v[200:203], v1 offset:41472
	ds_read_b128 v[204:207], v1 offset:41504
	ds_read_b128 v[208:211], v1 offset:41536
	ds_read_b128 v[212:215], v1 offset:41568
	v_add_f32_e32 v0, v0, v98
	s_waitcnt lgkmcnt(0)
	v_xor_b32_e32 v96, 0x80000000, v0
	v_pk_add_f32 v[2:3], v[2:3], v[98:99] op_sel_hi:[1,0] neg_lo:[0,1] neg_hi:[0,1]
	v_pk_add_f32 v[64:65], v[64:65], v[98:99] op_sel_hi:[1,0] neg_lo:[0,1] neg_hi:[0,1]
	v_pk_add_f32 v[4:5], v[4:5], v[98:99] op_sel_hi:[1,0] neg_lo:[0,1] neg_hi:[0,1]
	v_pk_add_f32 v[66:67], v[66:67], v[98:99] op_sel_hi:[1,0] neg_lo:[0,1] neg_hi:[0,1]
	v_pk_add_f32 v[6:7], v[6:7], v[98:99] op_sel_hi:[1,0] neg_lo:[0,1] neg_hi:[0,1]
	v_pk_add_f32 v[68:69], v[68:69], v[98:99] op_sel_hi:[1,0] neg_lo:[0,1] neg_hi:[0,1]
	v_pk_add_f32 v[8:9], v[8:9], v[98:99] op_sel_hi:[1,0] neg_lo:[0,1] neg_hi:[0,1]
	v_pk_add_f32 v[70:71], v[70:71], v[98:99] op_sel_hi:[1,0] neg_lo:[0,1] neg_hi:[0,1]
	v_pk_add_f32 v[10:11], v[10:11], v[98:99] op_sel_hi:[1,0] neg_lo:[0,1] neg_hi:[0,1]
	v_pk_add_f32 v[72:73], v[72:73], v[98:99] op_sel_hi:[1,0] neg_lo:[0,1] neg_hi:[0,1]
	v_pk_add_f32 v[12:13], v[12:13], v[98:99] op_sel_hi:[1,0] neg_lo:[0,1] neg_hi:[0,1]
	v_pk_add_f32 v[74:75], v[74:75], v[98:99] op_sel_hi:[1,0] neg_lo:[0,1] neg_hi:[0,1]
	v_pk_add_f32 v[14:15], v[14:15], v[98:99] op_sel_hi:[1,0] neg_lo:[0,1] neg_hi:[0,1]
	v_pk_add_f32 v[76:77], v[76:77], v[98:99] op_sel_hi:[1,0] neg_lo:[0,1] neg_hi:[0,1]
	v_pk_add_f32 v[16:17], v[16:17], v[98:99] op_sel_hi:[1,0] neg_lo:[0,1] neg_hi:[0,1]
	v_pk_add_f32 v[78:79], v[78:79], v[98:99] op_sel_hi:[1,0] neg_lo:[0,1] neg_hi:[0,1]
	v_mov_b32_e32 v97, v96
	v_mov_b32_e32 v98, v96
	v_mov_b32_e32 v99, v96
	v_mov_b32_e32 v100, v96
	v_mov_b32_e32 v101, v96
	v_mov_b32_e32 v102, v96
	v_mov_b32_e32 v103, v96
	v_mov_b32_e32 v104, v96
	v_mov_b32_e32 v105, v96
	v_mov_b32_e32 v106, v96
	v_mov_b32_e32 v107, v96
	v_mov_b32_e32 v108, v96
	v_mov_b32_e32 v109, v96
	v_mov_b32_e32 v110, v96
	v_mov_b32_e32 v111, v96
	v_mul_f32_e32 v163, v163, v115
	s_waitcnt lgkmcnt(0)
	v_pk_mul_f32 v[46:47], v[46:47], v[214:215]
	v_pk_mul_f32 v[42:43], v[42:43], v[210:211]
	v_pk_mul_f32 v[38:39], v[38:39], v[206:207]
	v_pk_mul_f32 v[34:35], v[34:35], v[202:203]
	v_pk_mul_f32 v[44:45], v[44:45], v[212:213]
	v_pk_mul_f32 v[40:41], v[40:41], v[208:209]
	v_pk_mul_f32 v[36:37], v[36:37], v[204:205]
	v_pk_mul_f32 v[32:33], v[32:33], v[200:201]
	v_pk_mul_f32 v[62:63], v[62:63], v[214:215]
	v_pk_mul_f32 v[58:59], v[58:59], v[210:211]
	v_pk_mul_f32 v[54:55], v[54:55], v[206:207]
	v_pk_mul_f32 v[50:51], v[50:51], v[202:203]
	v_pk_mul_f32 v[60:61], v[60:61], v[212:213]
	v_pk_mul_f32 v[56:57], v[56:57], v[208:209]
	v_pk_mul_f32 v[52:53], v[52:53], v[204:205]
	v_pk_mul_f32 v[48:49], v[48:49], v[200:201]

.LBB0_427:
	s_andn2_b64 vcc, exec, s[0:1]
	s_cbranch_vccnz .LBB0_444
	s_cmp_gt_i32 s20, 0x81ff
	s_cbranch_scc1 .LBB0_444
	s_waitcnt lgkmcnt(0)
	v_readlane_b32 s21, v253, 40
	v_readlane_b32 s34, v251, 37
	v_readlane_b32 s35, v251, 38
	v_readlane_b32 s36, v251, 39
	v_readlane_b32 s37, v251, 40
	v_readlane_b32 s38, v253, 23
	v_readlane_b32 s39, v253, 24
	v_readlane_b32 s0, v254, 48
	v_readlane_b32 s1, v254, 49
	v_readlane_b32 s2, v254, 50
	v_readlane_b32 s3, v254, 51
	v_readlane_b32 s4, v254, 60
	v_readlane_b32 s5, v254, 61
	v_readlane_b32 s10, v254, 62
	v_readlane_b32 s11, v254, 63
	v_readlane_b32 s16, v254, 52
	v_readlane_b32 s17, v254, 53
	s_mov_b32 s40, -1
	s_mov_b32 s41, 0xffff
	s_mov_b32 s42, -1
	s_mov_b32 s43, 0
	s_movk_i32 s44, 0xff
	s_mov_b32 s45, 0
	v_lshlrev_b32_e32 v152, 4, v189
	v_lshlrev_b32_e32 v153, 1, v189
	v_lshlrev_b32_e32 v154, 2, v189
	v_lshlrev_b32_e32 v155, 5, v189
	v_and_b32_e32 v116, 7, v189
	v_lshlrev_b32_e32 v116, 5, v116
	v_mov_b32_e32 v48, 0
	v_mov_b32_e32 v49, 0
	v_mov_b32_e32 v50, 0
	v_mov_b32_e32 v51, 0
	v_mov_b32_e32 v52, 0
	v_mov_b32_e32 v53, 0
	v_mov_b32_e32 v54, 0
	v_mov_b32_e32 v55, 0
	v_mov_b32_e32 v56, 0
	v_mov_b32_e32 v57, 0
	v_mov_b32_e32 v58, 0
	v_mov_b32_e32 v59, 0
	v_mov_b32_e32 v60, 0
	v_mov_b32_e32 v61, 0
	v_mov_b32_e32 v62, 0
	v_mov_b32_e32 v63, 0
	v_mov_b32_e32 v80, 0
	v_mov_b32_e32 v0, 0
	v_mov_b32_e32 v1, 0
	v_mov_b32_e32 v2, 0
	v_mov_b32_e32 v3, 0
	v_mov_b32_e32 v4, 0
	v_mov_b32_e32 v5, 0
	v_mov_b32_e32 v6, 0
	v_mov_b32_e32 v7, 0
	v_mov_b32_e32 v20, 0
	v_mov_b32_e32 v21, 0
	v_mov_b32_e32 v22, 0
	v_mov_b32_e32 v23, 0
	v_mov_b32_e32 v24, 0
	v_mov_b32_e32 v25, 0
	v_mov_b32_e32 v26, 0
	v_mov_b32_e32 v27, 0
	v_mov_b32_e32 v84, 0
	v_mov_b32_e32 v85, 0
	v_mov_b32_e32 v86, 0
	v_mov_b32_e32 v87, 0
	v_mov_b32_e32 v88, 0
	v_mov_b32_e32 v89, 0
	v_mov_b32_e32 v90, 0
	v_mov_b32_e32 v91, 0
	v_mov_b32_e32 v16, 0
	v_mov_b32_e32 v36, 0
	v_mov_b32_e32 v100, 0
	s_mov_b64 exec, s[40:41]
	global_load_dwordx4 v[48:51], v155, s[0:1]
	global_load_dwordx4 v[52:55], v155, s[0:1] offset:16
	s_mov_b64 exec, s[42:43]
	global_load_dwordx4 v[56:59], v155, s[2:3]
	global_load_dwordx4 v[60:63], v155, s[2:3] offset:16
	s_mov_b64 exec, -1
	global_load_dwordx4 v[64:67], v116, s[4:5]
	global_load_dwordx4 v[68:71], v116, s[4:5] offset:16
	global_load_dwordx4 v[72:75], v116, s[10:11]
	global_load_dwordx4 v[76:79], v116, s[10:11] offset:16
	s_mov_b64 exec, s[44:45]
	global_load_dword v80, v154, s[16:17]
	s_mov_b64 exec, -1
	s_mov_b32 s12, s20
	s_add_u32 s13, s20, s21
	s_mov_b32 s2, s12
	s_mul_i32 s2, s2, 0x1200
	s_add_u32 s2, s2, 0xe120000
	v_add_u32_e32 v17, s2, v152
	s_add_u32 s3, s2, 0x1140
	v_add_u32_e32 v155, s3, v153
	s_mov_b64 exec, s[40:41]
	global_load_dwordx4 v[0:3], v17, s[70:71]
	s_mov_b64 exec, s[42:43]
	global_load_dwordx4 v[4:7], v17, s[70:71] offset:768
	s_mov_b64 exec, -1
	global_load_dwordx4 v[8:11], v17, s[70:71] offset:1344
	global_load_dwordx4 v[12:15], v17, s[70:71] offset:2368
	s_mov_b64 exec, s[44:45]
	global_load_ushort v16, v155, s[70:71]
	s_mov_b64 exec, -1
	s_cmp_lt_u32 s13, 0x8200
	s_cselect_b32 s2, s13, s12
	s_add_u32 s13, s13, s21
	s_mul_i32 s2, s2, 0x1200
	s_add_u32 s2, s2, 0xe120000
	v_add_u32_e32 v37, s2, v152
	s_add_u32 s3, s2, 0x1140
	v_add_u32_e32 v155, s3, v153
	s_mov_b64 exec, s[40:41]
	global_load_dwordx4 v[20:23], v37, s[70:71]
	s_mov_b64 exec, s[42:43]
	global_load_dwordx4 v[24:27], v37, s[70:71] offset:768
	s_mov_b64 exec, -1
	global_load_dwordx4 v[28:31], v37, s[70:71] offset:1344
	global_load_dwordx4 v[32:35], v37, s[70:71] offset:2368
	s_mov_b64 exec, s[44:45]
	global_load_ushort v36, v155, s[70:71]
	s_mov_b64 exec, -1
	s_cmp_lt_u32 s13, 0x8200
	s_cselect_b32 s2, s13, s12
	s_add_u32 s13, s13, s21
	s_mul_i32 s2, s2, 0x1200
	s_add_u32 s2, s2, 0xe120000
	v_add_u32_e32 v101, s2, v152
	s_add_u32 s3, s2, 0x1140
	v_add_u32_e32 v155, s3, v153
	s_mov_b64 exec, s[40:41]
	global_load_dwordx4 v[84:87], v101, s[70:71]
	s_mov_b64 exec, s[42:43]
	global_load_dwordx4 v[88:91], v101, s[70:71] offset:768
	s_mov_b64 exec, -1
	global_load_dwordx4 v[92:95], v101, s[70:71] offset:1344
	global_load_dwordx4 v[96:99], v101, s[70:71] offset:2368
	s_mov_b64 exec, s[44:45]
	global_load_ushort v100, v155, s[70:71]
	s_mov_b64 exec, -1
	s_waitcnt vmcnt(10)
	s_mul_i32 s2, s12, 0x300
	v_add_u32_e32 v116, s2, v152
	s_lshl_b32 s2, s12, 9
	v_add_u32_e32 v117, s2, v152
	s_lshl_b32 s2, s12, 5
	v_add_u32_e32 v118, s2, v154
	s_mov_b32 s11, s13
	v_lshlrev_b32_e32 v104, 16, v0
	v_and_b32_e32 v105, 0xffff0000, v0
	v_lshlrev_b32_e32 v106, 16, v1
	v_and_b32_e32 v107, 0xffff0000, v1
	v_lshlrev_b32_e32 v108, 16, v2
	v_and_b32_e32 v109, 0xffff0000, v2
	v_lshlrev_b32_e32 v110, 16, v3
	v_and_b32_e32 v111, 0xffff0000, v3
	v_mul_f32_e32 v140, v104, v104
	v_fmac_f32_e32 v140, v105, v105
	v_fmac_f32_e32 v140, v106, v106
	v_fmac_f32_e32 v140, v107, v107
	v_fmac_f32_e32 v140, v108, v108
	v_fmac_f32_e32 v140, v109, v109
	v_fmac_f32_e32 v140, v110, v110
	v_fmac_f32_e32 v140, v111, v111
	s_nop 1
	v_add_f32_dpp v140, v140, v140 quad_perm:[1,0,3,2] row_mask:0xf bank_mask:0xf
	s_nop 1
	v_add_f32_dpp v140, v140, v140 quad_perm:[2,3,0,1] row_mask:0xf bank_mask:0xf
	s_nop 1
	v_add_f32_dpp v140, v140, v140 row_half_mirror row_mask:0xf bank_mask:0xf
	s_nop 1
	v_add_f32_dpp v140, v140, v140 row_mirror row_mask:0xf bank_mask:0xf
	s_nop 1
	v_add_f32_dpp v140, v140, v140 row_bcast:15 row_mask:0xa bank_mask:0xf
	s_nop 1
	v_add_f32_dpp v140, v140, v140 row_bcast:31 row_mask:0xc bank_mask:0xf
	s_nop 1
	v_readlane_b32 s10, v140, 63
	s_nop 3
	v_mov_b32_e32 v142, s10
	v_fmamk_f32 v142, v142, 0x3b2aaaab, v172
	v_rsq_f32_e32 v142, v142
	s_nop 0
	v_pk_mul_f32 v[104:105], v[104:105], v[142:143] op_sel_hi:[1,0]
	v_pk_mul_f32 v[106:107], v[106:107], v[142:143] op_sel_hi:[1,0]
	v_pk_mul_f32 v[108:109], v[108:109], v[142:143] op_sel_hi:[1,0]
	v_pk_mul_f32 v[110:111], v[110:111], v[142:143] op_sel_hi:[1,0]
	v_pk_mul_f32 v[104:105], v[104:105], v[48:49]
	v_pk_mul_f32 v[106:107], v[106:107], v[50:51]
	v_pk_mul_f32 v[108:109], v[108:109], v[52:53]
	v_pk_mul_f32 v[110:111], v[110:111], v[54:55]
	v_cvt_pk_bf16_f32 v148, v104, v105
	v_cvt_pk_bf16_f32 v149, v106, v107
	v_cvt_pk_bf16_f32 v150, v108, v109
	v_cvt_pk_bf16_f32 v151, v110, v111
	s_mov_b64 exec, s[40:41]
	global_store_dwordx4 v116, v[148:151], s[34:35]
	s_mov_b64 exec, -1
	v_lshlrev_b32_e32 v104, 16, v4
	v_and_b32_e32 v105, 0xffff0000, v4
	v_lshlrev_b32_e32 v106, 16, v5
	v_and_b32_e32 v107, 0xffff0000, v5
	v_lshlrev_b32_e32 v108, 16, v6
	v_and_b32_e32 v109, 0xffff0000, v6
	v_lshlrev_b32_e32 v110, 16, v7
	v_and_b32_e32 v111, 0xffff0000, v7
	v_mul_f32_e32 v140, v104, v104
	v_fmac_f32_e32 v140, v105, v105
	v_fmac_f32_e32 v140, v106, v106
	v_fmac_f32_e32 v140, v107, v107
	v_fmac_f32_e32 v140, v108, v108
	v_fmac_f32_e32 v140, v109, v109
	v_fmac_f32_e32 v140, v110, v110
	v_fmac_f32_e32 v140, v111, v111
	s_nop 1
	v_add_f32_dpp v140, v140, v140 quad_perm:[1,0,3,2] row_mask:0xf bank_mask:0xf
	s_nop 1
	v_add_f32_dpp v140, v140, v140 quad_perm:[2,3,0,1] row_mask:0xf bank_mask:0xf
	s_nop 1
	v_add_f32_dpp v140, v140, v140 row_half_mirror row_mask:0xf bank_mask:0xf
	s_nop 1
	v_add_f32_dpp v140, v140, v140 row_mirror row_mask:0xf bank_mask:0xf
	s_nop 1
	v_add_f32_dpp v140, v140, v140 row_bcast:15 row_mask:0xa bank_mask:0xf
	s_nop 1
	v_add_f32_dpp v140, v140, v140 row_bcast:31 row_mask:0xc bank_mask:0xf
	s_nop 1
	v_readlane_b32 s10, v140, 63
	s_nop 3
	v_mov_b32_e32 v142, s10
	v_fmamk_f32 v142, v142, 0x3b800000, v172
	v_rsq_f32_e32 v142, v142
	s_nop 0
	v_pk_mul_f32 v[104:105], v[104:105], v[142:143] op_sel_hi:[1,0]
	v_pk_mul_f32 v[106:107], v[106:107], v[142:143] op_sel_hi:[1,0]
	v_pk_mul_f32 v[108:109], v[108:109], v[142:143] op_sel_hi:[1,0]
	v_pk_mul_f32 v[110:111], v[110:111], v[142:143] op_sel_hi:[1,0]
	v_pk_mul_f32 v[104:105], v[104:105], v[56:57]
	v_pk_mul_f32 v[106:107], v[106:107], v[58:59]
	v_pk_mul_f32 v[108:109], v[108:109], v[60:61]
	v_pk_mul_f32 v[110:111], v[110:111], v[62:63]
	v_cvt_pk_bf16_f32 v148, v104, v105
	v_cvt_pk_bf16_f32 v149, v106, v107
	v_cvt_pk_bf16_f32 v150, v108, v109
	v_cvt_pk_bf16_f32 v151, v110, v111
	s_mov_b64 exec, s[42:43]
	global_store_dwordx4 v117, v[148:151], s[36:37]
	s_mov_b64 exec, -1
	v_lshlrev_b32_e32 v104, 16, v8
	v_and_b32_e32 v105, 0xffff0000, v8
	v_lshlrev_b32_e32 v106, 16, v9
	v_and_b32_e32 v107, 0xffff0000, v9
	v_lshlrev_b32_e32 v108, 16, v10
	v_and_b32_e32 v109, 0xffff0000, v10
	v_lshlrev_b32_e32 v110, 16, v11
	v_and_b32_e32 v111, 0xffff0000, v11
	v_mul_f32_e32 v140, v104, v104
	v_fmac_f32_e32 v140, v105, v105
	v_fmac_f32_e32 v140, v106, v106
	v_fmac_f32_e32 v140, v107, v107
	v_fmac_f32_e32 v140, v108, v108
	v_fmac_f32_e32 v140, v109, v109
	v_fmac_f32_e32 v140, v110, v110
	v_fmac_f32_e32 v140, v111, v111
	s_nop 1
	v_add_f32_dpp v140, v140, v140 quad_perm:[1,0,3,2] row_mask:0xf bank_mask:0xf
	s_nop 1
	v_add_f32_dpp v140, v140, v140 quad_perm:[2,3,0,1] row_mask:0xf bank_mask:0xf
	s_nop 1
	v_add_f32_dpp v140, v140, v140 row_half_mirror row_mask:0xf bank_mask:0xf
	v_fmamk_f32 v142, v140, 0x3c800000, v172
	v_rsq_f32_e32 v142, v142
	s_nop 0
	v_mul_f32_e32 v142, 0x3e38aa3b, v142
	v_pk_mul_f32 v[104:105], v[104:105], v[142:143] op_sel_hi:[1,0]
	v_pk_mul_f32 v[106:107], v[106:107], v[142:143] op_sel_hi:[1,0]
	v_pk_mul_f32 v[108:109], v[108:109], v[142:143] op_sel_hi:[1,0]
	v_pk_mul_f32 v[110:111], v[110:111], v[142:143] op_sel_hi:[1,0]
	v_pk_mul_f32 v[104:105], v[104:105], v[64:65]
	v_pk_mul_f32 v[106:107], v[106:107], v[66:67]
	v_pk_mul_f32 v[108:109], v[108:109], v[68:69]
	v_pk_mul_f32 v[110:111], v[110:111], v[70:71]
	v_cvt_pk_bf16_f32 v148, v104, v105
	v_cvt_pk_bf16_f32 v149, v106, v107
	v_cvt_pk_bf16_f32 v150, v108, v109
	v_cvt_pk_bf16_f32 v151, v110, v111
	global_store_dwordx4 v17, v[148:151], s[70:71] offset:1344
	v_lshlrev_b32_e32 v104, 16, v12
	v_and_b32_e32 v105, 0xffff0000, v12
	v_lshlrev_b32_e32 v106, 16, v13
	v_and_b32_e32 v107, 0xffff0000, v13
	v_lshlrev_b32_e32 v108, 16, v14
	v_and_b32_e32 v109, 0xffff0000, v14
	v_lshlrev_b32_e32 v110, 16, v15
	v_and_b32_e32 v111, 0xffff0000, v15
	v_mul_f32_e32 v140, v104, v104
	v_fmac_f32_e32 v140, v105, v105
	v_fmac_f32_e32 v140, v106, v106
	v_fmac_f32_e32 v140, v107, v107
	v_fmac_f32_e32 v140, v108, v108
	v_fmac_f32_e32 v140, v109, v109
	v_fmac_f32_e32 v140, v110, v110
	v_fmac_f32_e32 v140, v111, v111
	s_nop 1
	v_add_f32_dpp v140, v140, v140 quad_perm:[1,0,3,2] row_mask:0xf bank_mask:0xf
	s_nop 1
	v_add_f32_dpp v140, v140, v140 quad_perm:[2,3,0,1] row_mask:0xf bank_mask:0xf
	s_nop 1
	v_add_f32_dpp v140, v140, v140 row_half_mirror row_mask:0xf bank_mask:0xf
	v_fmamk_f32 v142, v140, 0x3c800000, v172
	v_rsq_f32_e32 v142, v142
	s_nop 0
	v_pk_mul_f32 v[104:105], v[104:105], v[142:143] op_sel_hi:[1,0]
	v_pk_mul_f32 v[106:107], v[106:107], v[142:143] op_sel_hi:[1,0]
	v_pk_mul_f32 v[108:109], v[108:109], v[142:143] op_sel_hi:[1,0]
	v_pk_mul_f32 v[110:111], v[110:111], v[142:143] op_sel_hi:[1,0]
	v_pk_mul_f32 v[104:105], v[104:105], v[72:73]
	v_pk_mul_f32 v[106:107], v[106:107], v[74:75]
	v_pk_mul_f32 v[108:109], v[108:109], v[76:77]
	v_pk_mul_f32 v[110:111], v[110:111], v[78:79]
	v_cvt_pk_bf16_f32 v148, v104, v105
	v_cvt_pk_bf16_f32 v149, v106, v107
	v_cvt_pk_bf16_f32 v150, v108, v109
	v_cvt_pk_bf16_f32 v151, v110, v111
	global_store_dwordx4 v17, v[148:151], s[70:71] offset:2368
	s_mul_hi_i32 s2, s12, 0x7e07e07f
	s_lshr_b32 s3, s2, 31
	s_ashr_i32 s2, s2, 12
	s_add_i32 s2, s2, s3
	s_mulk_i32 s2, 0x2080
	s_sub_i32 s2, s12, s2
	s_mov_b64 exec, s[44:45]
	v_mov_b32_e32 v120, 0
	s_cmpk_lt_i32 s2, 0x70
	s_cbranch_scc1 .Lpa_p0_pad
	s_mov_b32 s13, 0xbfb8aa3b
	v_lshlrev_b32_e32 v120, 16, v16
	v_mov_b32_e32 v121, v80
	v_add_f32_e32 v121, v121, v120
	v_min_f32_e32 v120, 0, v121
	v_mul_f32_e64 v121, |v121|, s13
	v_exp_f32_e32 v121, v121
	s_mov_b32 s13, 0x3f2aaaab
	v_add_f32_e32 v124, 1.0, v121
	v_add_f32_e32 v122, -1.0, v124
	v_sub_f32_e32 v123, v122, v124
	v_add_f32_e32 v123, 1.0, v123
	v_sub_f32_e32 v122, v121, v122
	v_add_f32_e32 v125, v122, v123
	v_frexp_mant_f32_e32 v122, v124
	v_cmp_gt_f32_e32 vcc, s13, v122
	v_cvt_f64_f32_e32 v[122:123], v124
	v_frexp_exp_i32_f64_e32 v122, v[122:123]
	v_subbrev_co_u32_e32 v130, vcc, 0, v122, vcc
	v_sub_u32_e32 v122, 0, v130
	v_ldexp_f32 v123, v124, v122
	v_add_f32_e32 v124, -1.0, v123
	v_add_f32_e32 v126, 1.0, v123
	v_ldexp_f32 v122, v125, v122
	v_add_f32_e32 v125, 1.0, v124
	v_add_f32_e32 v127, -1.0, v126
	v_sub_f32_e32 v125, v123, v125
	v_sub_f32_e32 v123, v123, v127
	v_add_f32_e32 v125, v122, v125
	v_add_f32_e32 v122, v122, v123
	v_add_f32_e32 v131, v126, v122
	v_rcp_f32_e32 v133, v131
	v_sub_f32_e32 v123, v131, v126
	v_sub_f32_e32 v132, v122, v123
	v_add_f32_e32 v123, v124, v125
	v_mul_f32_e32 v135, v123, v133
	v_sub_f32_e32 v122, v123, v124
	v_mul_f32_e32 v124, v131, v135
	v_fma_f32 v126, v135, v131, -v124
	v_fmac_f32_e32 v126, v135, v132
	v_sub_f32_e32 v134, v125, v122
	v_add_f32_e32 v122, v124, v126
	v_sub_f32_e32 v125, v123, v122
	v_pk_add_f32 v[128:129], v[122:123], v[124:125] neg_lo:[0,1] neg_hi:[0,1]
	v_mov_b32_e32 v127, v122
	v_pk_add_f32 v[122:123], v[128:129], v[126:127] neg_lo:[0,1] neg_hi:[0,1]
	s_mov_b32 s13, 0x3f317218
	v_add_f32_e32 v123, v134, v123
	v_add_f32_e32 v122, v122, v123
	v_add_f32_e32 v123, v125, v122
	v_mul_f32_e32 v134, v133, v123
	v_mul_f32_e32 v124, v131, v134
	v_fma_f32 v126, v134, v131, -v124
	v_fmac_f32_e32 v126, v134, v132
	v_sub_f32_e32 v125, v125, v123
	v_add_f32_e32 v131, v122, v125
	v_add_f32_e32 v122, v124, v126
	v_sub_f32_e32 v125, v123, v122
	v_pk_add_f32 v[128:129], v[122:123], v[124:125] neg_lo:[0,1] neg_hi:[0,1]
	v_mov_b32_e32 v127, v122
	v_pk_add_f32 v[122:123], v[128:129], v[126:127] neg_lo:[0,1] neg_hi:[0,1]
	s_nop 0
	v_add_f32_e32 v123, v131, v123
	v_add_f32_e32 v122, v122, v123
	v_add_f32_e32 v123, v135, v134
	v_add_f32_e32 v122, v125, v122
	v_sub_f32_e32 v124, v123, v135
	v_mul_f32_e32 v122, v133, v122
	v_sub_f32_e32 v124, v134, v124
	v_add_f32_e32 v124, v124, v122
	v_add_f32_e32 v126, v123, v124
	v_mul_f32_e32 v127, v126, v126
	v_mov_b32_e32 v122, 0x3ecc95a3
	v_fmamk_f32 v122, v127, 0x3e9b6dac, v122
	v_fmaak_f32 v165, v127, v122, 0x3f2aaada
	v_cvt_f32_i32_e32 v122, v130
	v_sub_f32_e32 v123, v126, v123
	v_sub_f32_e32 v123, v124, v123
	v_ldexp_f32 v128, v123, 1
	v_mul_f32_e32 v123, v126, v127
	v_ldexp_f32 v125, v126, 1
	v_pk_mul_f32 v[126:127], v[122:123], v[164:165]
	s_nop 0
	v_fma_f32 v124, v122, s13, -v126
	v_fmac_f32_e32 v124, 0xb102e308, v122
	v_pk_add_f32 v[122:123], v[126:127], v[124:125]
	s_mov_b32 s13, 0x7f800000
	v_sub_f32_e32 v125, v123, v125
	v_sub_f32_e32 v125, v127, v125
	v_add_f32_e32 v129, v128, v125
	v_mov_b32_e32 v128, v126
	v_pk_add_f32 v[126:127], v[122:123], v[126:127] neg_lo:[0,1] neg_hi:[0,1]
	v_pk_add_f32 v[130:131], v[122:123], v[128:129]
	v_mov_b32_e32 v125, v122
	v_mov_b32_e32 v127, v131
	v_pk_add_f32 v[132:133], v[124:125], v[126:127] neg_lo:[0,1] neg_hi:[0,1]
	v_pk_add_f32 v[124:125], v[124:125], v[126:127]
	v_mov_b32_e32 v128, v129
	v_pk_add_f32 v[126:127], v[124:125], v[122:123] op_sel:[1,0] op_sel_hi:[0,1] neg_lo:[0,1] neg_hi:[0,1]
	v_pk_add_f32 v[134:135], v[130:131], v[126:127] op_sel_hi:[1,0] neg_lo:[0,1] neg_hi:[0,1]
	v_mov_b32_e32 v130, v131
	v_mov_b32_e32 v131, v125
	v_pk_mov_b32 v[126:127], v[122:123], v[126:127] op_sel:[1,0]
	v_mov_b32_e32 v129, v122
	v_pk_add_f32 v[126:127], v[130:131], v[126:127] neg_lo:[0,1] neg_hi:[0,1]
	v_mov_b32_e32 v134, v132
	v_pk_add_f32 v[122:123], v[128:129], v[126:127] neg_lo:[0,1] neg_hi:[0,1]
	v_mov_b32_e32 v133, v125
	v_pk_add_f32 v[126:127], v[134:135], v[122:123]
	v_cmp_neq_f32_e32 vcc, s13, v121
	v_pk_add_f32 v[128:129], v[126:127], v[126:127] op_sel:[0,1] op_sel_hi:[1,0]
	s_mov_b32 s13, 0x33800000
	v_pk_add_f32 v[124:125], v[124:125], v[128:129] op_sel:[1,0] op_sel_hi:[0,1]
	v_mov_b32_e32 v127, v124
	v_pk_add_f32 v[130:131], v[126:127], v[132:133] neg_lo:[0,1] neg_hi:[0,1]
	v_mov_b32_e32 v123, v128
	v_sub_f32_e32 v125, v126, v130
	v_pk_add_f32 v[122:123], v[122:123], v[130:131] neg_lo:[0,1] neg_hi:[0,1]
	v_sub_f32_e32 v125, v132, v125
	v_add_f32_e32 v122, v122, v125
	v_add_f32_e32 v122, v122, v123
	v_add_f32_e32 v122, v124, v122
	v_cndmask_b32_e32 v122, v186, v122, vcc
	v_cmp_ngt_f32_e32 vcc, -1.0, v121
	s_nop 1
	v_cndmask_b32_e32 v122, v187, v122, vcc
	v_cmp_neq_f32_e32 vcc, -1.0, v121
	s_nop 1
	v_cndmask_b32_e32 v122, v188, v122, vcc
	v_cmp_lt_f32_e64 vcc, |v121|, s13
	s_nop 1
	v_cndmask_b32_e32 v121, v122, v121, vcc
	v_sub_f32_e32 v120, v120, v121
.Lpa_p0_pad:
	global_store_dword v118, v120, s[38:39]
	s_mov_b64 exec, -1
	s_mov_b32 s13, s11
	s_cmp_lt_u32 s13, 0x8200
	s_cselect_b32 s2, s13, s12
	s_add_u32 s13, s13, s21
	s_mul_i32 s2, s2, 0x1200
	s_add_u32 s2, s2, 0xe120000
	v_add_u32_e32 v17, s2, v152
	s_add_u32 s3, s2, 0x1140
	v_add_u32_e32 v155, s3, v153
	s_mov_b64 exec, s[40:41]
	global_load_dwordx4 v[0:3], v17, s[70:71]
	s_mov_b64 exec, s[42:43]
	global_load_dwordx4 v[4:7], v17, s[70:71] offset:768
	s_mov_b64 exec, -1
	global_load_dwordx4 v[8:11], v17, s[70:71] offset:1344
	global_load_dwordx4 v[12:15], v17, s[70:71] offset:2368
	s_mov_b64 exec, s[44:45]
	global_load_ushort v16, v155, s[70:71]
	s_mov_b64 exec, -1
	s_add_u32 s12, s12, s21
	s_cmp_gt_u32 s12, 0x81ff
	s_cbranch_scc1 .Lpa_done
	s_waitcnt vmcnt(15)
	s_mul_i32 s2, s12, 0x300
	v_add_u32_e32 v116, s2, v152
	s_lshl_b32 s2, s12, 9
	v_add_u32_e32 v117, s2, v152
	s_lshl_b32 s2, s12, 5
	v_add_u32_e32 v118, s2, v154
	s_mov_b32 s11, s13
	v_lshlrev_b32_e32 v104, 16, v20
	v_and_b32_e32 v105, 0xffff0000, v20
	v_lshlrev_b32_e32 v106, 16, v21
	v_and_b32_e32 v107, 0xffff0000, v21
	v_lshlrev_b32_e32 v108, 16, v22
	v_and_b32_e32 v109, 0xffff0000, v22
	v_lshlrev_b32_e32 v110, 16, v23
	v_and_b32_e32 v111, 0xffff0000, v23
	v_mul_f32_e32 v140, v104, v104
	v_fmac_f32_e32 v140, v105, v105
	v_fmac_f32_e32 v140, v106, v106
	v_fmac_f32_e32 v140, v107, v107
	v_fmac_f32_e32 v140, v108, v108
	v_fmac_f32_e32 v140, v109, v109
	v_fmac_f32_e32 v140, v110, v110
	v_fmac_f32_e32 v140, v111, v111
	s_nop 1
	v_add_f32_dpp v140, v140, v140 quad_perm:[1,0,3,2] row_mask:0xf bank_mask:0xf
	s_nop 1
	v_add_f32_dpp v140, v140, v140 quad_perm:[2,3,0,1] row_mask:0xf bank_mask:0xf
	s_nop 1
	v_add_f32_dpp v140, v140, v140 row_half_mirror row_mask:0xf bank_mask:0xf
	s_nop 1
	v_add_f32_dpp v140, v140, v140 row_mirror row_mask:0xf bank_mask:0xf
	s_nop 1
	v_add_f32_dpp v140, v140, v140 row_bcast:15 row_mask:0xa bank_mask:0xf
	s_nop 1
	v_add_f32_dpp v140, v140, v140 row_bcast:31 row_mask:0xc bank_mask:0xf
	s_nop 1
	v_readlane_b32 s10, v140, 63
	s_nop 3
	v_mov_b32_e32 v142, s10
	v_fmamk_f32 v142, v142, 0x3b2aaaab, v172
	v_rsq_f32_e32 v142, v142
	s_nop 0
	v_pk_mul_f32 v[104:105], v[104:105], v[142:143] op_sel_hi:[1,0]
	v_pk_mul_f32 v[106:107], v[106:107], v[142:143] op_sel_hi:[1,0]
	v_pk_mul_f32 v[108:109], v[108:109], v[142:143] op_sel_hi:[1,0]
	v_pk_mul_f32 v[110:111], v[110:111], v[142:143] op_sel_hi:[1,0]
	v_pk_mul_f32 v[104:105], v[104:105], v[48:49]
	v_pk_mul_f32 v[106:107], v[106:107], v[50:51]
	v_pk_mul_f32 v[108:109], v[108:109], v[52:53]
	v_pk_mul_f32 v[110:111], v[110:111], v[54:55]
	v_cvt_pk_bf16_f32 v148, v104, v105
	v_cvt_pk_bf16_f32 v149, v106, v107
	v_cvt_pk_bf16_f32 v150, v108, v109
	v_cvt_pk_bf16_f32 v151, v110, v111
	s_mov_b64 exec, s[40:41]
	global_store_dwordx4 v116, v[148:151], s[34:35]
	s_mov_b64 exec, -1
	v_lshlrev_b32_e32 v104, 16, v24
	v_and_b32_e32 v105, 0xffff0000, v24
	v_lshlrev_b32_e32 v106, 16, v25
	v_and_b32_e32 v107, 0xffff0000, v25
	v_lshlrev_b32_e32 v108, 16, v26
	v_and_b32_e32 v109, 0xffff0000, v26
	v_lshlrev_b32_e32 v110, 16, v27
	v_and_b32_e32 v111, 0xffff0000, v27
	v_mul_f32_e32 v140, v104, v104
	v_fmac_f32_e32 v140, v105, v105
	v_fmac_f32_e32 v140, v106, v106
	v_fmac_f32_e32 v140, v107, v107
	v_fmac_f32_e32 v140, v108, v108
	v_fmac_f32_e32 v140, v109, v109
	v_fmac_f32_e32 v140, v110, v110
	v_fmac_f32_e32 v140, v111, v111
	s_nop 1
	v_add_f32_dpp v140, v140, v140 quad_perm:[1,0,3,2] row_mask:0xf bank_mask:0xf
	s_nop 1
	v_add_f32_dpp v140, v140, v140 quad_perm:[2,3,0,1] row_mask:0xf bank_mask:0xf
	s_nop 1
	v_add_f32_dpp v140, v140, v140 row_half_mirror row_mask:0xf bank_mask:0xf
	s_nop 1
	v_add_f32_dpp v140, v140, v140 row_mirror row_mask:0xf bank_mask:0xf
	s_nop 1
	v_add_f32_dpp v140, v140, v140 row_bcast:15 row_mask:0xa bank_mask:0xf
	s_nop 1
	v_add_f32_dpp v140, v140, v140 row_bcast:31 row_mask:0xc bank_mask:0xf
	s_nop 1
	v_readlane_b32 s10, v140, 63
	s_nop 3
	v_mov_b32_e32 v142, s10
	v_fmamk_f32 v142, v142, 0x3b800000, v172
	v_rsq_f32_e32 v142, v142
	s_nop 0
	v_pk_mul_f32 v[104:105], v[104:105], v[142:143] op_sel_hi:[1,0]
	v_pk_mul_f32 v[106:107], v[106:107], v[142:143] op_sel_hi:[1,0]
	v_pk_mul_f32 v[108:109], v[108:109], v[142:143] op_sel_hi:[1,0]
	v_pk_mul_f32 v[110:111], v[110:111], v[142:143] op_sel_hi:[1,0]
	v_pk_mul_f32 v[104:105], v[104:105], v[56:57]
	v_pk_mul_f32 v[106:107], v[106:107], v[58:59]
	v_pk_mul_f32 v[108:109], v[108:109], v[60:61]
	v_pk_mul_f32 v[110:111], v[110:111], v[62:63]
	v_cvt_pk_bf16_f32 v148, v104, v105
	v_cvt_pk_bf16_f32 v149, v106, v107
	v_cvt_pk_bf16_f32 v150, v108, v109
	v_cvt_pk_bf16_f32 v151, v110, v111
	s_mov_b64 exec, s[42:43]
	global_store_dwordx4 v117, v[148:151], s[36:37]
	s_mov_b64 exec, -1
	v_lshlrev_b32_e32 v104, 16, v28
	v_and_b32_e32 v105, 0xffff0000, v28
	v_lshlrev_b32_e32 v106, 16, v29
	v_and_b32_e32 v107, 0xffff0000, v29
	v_lshlrev_b32_e32 v108, 16, v30
	v_and_b32_e32 v109, 0xffff0000, v30
	v_lshlrev_b32_e32 v110, 16, v31
	v_and_b32_e32 v111, 0xffff0000, v31
	v_mul_f32_e32 v140, v104, v104
	v_fmac_f32_e32 v140, v105, v105
	v_fmac_f32_e32 v140, v106, v106
	v_fmac_f32_e32 v140, v107, v107
	v_fmac_f32_e32 v140, v108, v108
	v_fmac_f32_e32 v140, v109, v109
	v_fmac_f32_e32 v140, v110, v110
	v_fmac_f32_e32 v140, v111, v111
	s_nop 1
	v_add_f32_dpp v140, v140, v140 quad_perm:[1,0,3,2] row_mask:0xf bank_mask:0xf
	s_nop 1
	v_add_f32_dpp v140, v140, v140 quad_perm:[2,3,0,1] row_mask:0xf bank_mask:0xf
	s_nop 1
	v_add_f32_dpp v140, v140, v140 row_half_mirror row_mask:0xf bank_mask:0xf
	v_fmamk_f32 v142, v140, 0x3c800000, v172
	v_rsq_f32_e32 v142, v142
	s_nop 0
	v_mul_f32_e32 v142, 0x3e38aa3b, v142
	v_pk_mul_f32 v[104:105], v[104:105], v[142:143] op_sel_hi:[1,0]
	v_pk_mul_f32 v[106:107], v[106:107], v[142:143] op_sel_hi:[1,0]
	v_pk_mul_f32 v[108:109], v[108:109], v[142:143] op_sel_hi:[1,0]
	v_pk_mul_f32 v[110:111], v[110:111], v[142:143] op_sel_hi:[1,0]
	v_pk_mul_f32 v[104:105], v[104:105], v[64:65]
	v_pk_mul_f32 v[106:107], v[106:107], v[66:67]
	v_pk_mul_f32 v[108:109], v[108:109], v[68:69]
	v_pk_mul_f32 v[110:111], v[110:111], v[70:71]
	v_cvt_pk_bf16_f32 v148, v104, v105
	v_cvt_pk_bf16_f32 v149, v106, v107
	v_cvt_pk_bf16_f32 v150, v108, v109
	v_cvt_pk_bf16_f32 v151, v110, v111
	global_store_dwordx4 v37, v[148:151], s[70:71] offset:1344
	v_lshlrev_b32_e32 v104, 16, v32
	v_and_b32_e32 v105, 0xffff0000, v32
	v_lshlrev_b32_e32 v106, 16, v33
	v_and_b32_e32 v107, 0xffff0000, v33
	v_lshlrev_b32_e32 v108, 16, v34
	v_and_b32_e32 v109, 0xffff0000, v34
	v_lshlrev_b32_e32 v110, 16, v35
	v_and_b32_e32 v111, 0xffff0000, v35
	v_mul_f32_e32 v140, v104, v104
	v_fmac_f32_e32 v140, v105, v105
	v_fmac_f32_e32 v140, v106, v106
	v_fmac_f32_e32 v140, v107, v107
	v_fmac_f32_e32 v140, v108, v108
	v_fmac_f32_e32 v140, v109, v109
	v_fmac_f32_e32 v140, v110, v110
	v_fmac_f32_e32 v140, v111, v111
	s_nop 1
	v_add_f32_dpp v140, v140, v140 quad_perm:[1,0,3,2] row_mask:0xf bank_mask:0xf
	s_nop 1
	v_add_f32_dpp v140, v140, v140 quad_perm:[2,3,0,1] row_mask:0xf bank_mask:0xf
	s_nop 1
	v_add_f32_dpp v140, v140, v140 row_half_mirror row_mask:0xf bank_mask:0xf
	v_fmamk_f32 v142, v140, 0x3c800000, v172
	v_rsq_f32_e32 v142, v142
	s_nop 0
	v_pk_mul_f32 v[104:105], v[104:105], v[142:143] op_sel_hi:[1,0]
	v_pk_mul_f32 v[106:107], v[106:107], v[142:143] op_sel_hi:[1,0]
	v_pk_mul_f32 v[108:109], v[108:109], v[142:143] op_sel_hi:[1,0]
	v_pk_mul_f32 v[110:111], v[110:111], v[142:143] op_sel_hi:[1,0]
	v_pk_mul_f32 v[104:105], v[104:105], v[72:73]
	v_pk_mul_f32 v[106:107], v[106:107], v[74:75]
	v_pk_mul_f32 v[108:109], v[108:109], v[76:77]
	v_pk_mul_f32 v[110:111], v[110:111], v[78:79]
	v_cvt_pk_bf16_f32 v148, v104, v105
	v_cvt_pk_bf16_f32 v149, v106, v107
	v_cvt_pk_bf16_f32 v150, v108, v109
	v_cvt_pk_bf16_f32 v151, v110, v111
	global_store_dwordx4 v37, v[148:151], s[70:71] offset:2368
	s_mul_hi_i32 s2, s12, 0x7e07e07f
	s_lshr_b32 s3, s2, 31
	s_ashr_i32 s2, s2, 12
	s_add_i32 s2, s2, s3
	s_mulk_i32 s2, 0x2080
	s_sub_i32 s2, s12, s2
	s_mov_b64 exec, s[44:45]
	v_mov_b32_e32 v120, 0
	s_cmpk_lt_i32 s2, 0x70
	s_cbranch_scc1 .Lpa_p1_pad
	s_mov_b32 s13, 0xbfb8aa3b
	v_lshlrev_b32_e32 v120, 16, v36
	v_mov_b32_e32 v121, v80
	v_add_f32_e32 v121, v121, v120
	v_min_f32_e32 v120, 0, v121
	v_mul_f32_e64 v121, |v121|, s13
	v_exp_f32_e32 v121, v121
	s_mov_b32 s13, 0x3f2aaaab
	v_add_f32_e32 v124, 1.0, v121
	v_add_f32_e32 v122, -1.0, v124
	v_sub_f32_e32 v123, v122, v124
	v_add_f32_e32 v123, 1.0, v123
	v_sub_f32_e32 v122, v121, v122
	v_add_f32_e32 v125, v122, v123
	v_frexp_mant_f32_e32 v122, v124
	v_cmp_gt_f32_e32 vcc, s13, v122
	v_cvt_f64_f32_e32 v[122:123], v124
	v_frexp_exp_i32_f64_e32 v122, v[122:123]
	v_subbrev_co_u32_e32 v130, vcc, 0, v122, vcc
	v_sub_u32_e32 v122, 0, v130
	v_ldexp_f32 v123, v124, v122
	v_add_f32_e32 v124, -1.0, v123
	v_add_f32_e32 v126, 1.0, v123
	v_ldexp_f32 v122, v125, v122
	v_add_f32_e32 v125, 1.0, v124
	v_add_f32_e32 v127, -1.0, v126
	v_sub_f32_e32 v125, v123, v125
	v_sub_f32_e32 v123, v123, v127
	v_add_f32_e32 v125, v122, v125
	v_add_f32_e32 v122, v122, v123
	v_add_f32_e32 v131, v126, v122
	v_rcp_f32_e32 v133, v131
	v_sub_f32_e32 v123, v131, v126
	v_sub_f32_e32 v132, v122, v123
	v_add_f32_e32 v123, v124, v125
	v_mul_f32_e32 v135, v123, v133
	v_sub_f32_e32 v122, v123, v124
	v_mul_f32_e32 v124, v131, v135
	v_fma_f32 v126, v135, v131, -v124
	v_fmac_f32_e32 v126, v135, v132
	v_sub_f32_e32 v134, v125, v122
	v_add_f32_e32 v122, v124, v126
	v_sub_f32_e32 v125, v123, v122
	v_pk_add_f32 v[128:129], v[122:123], v[124:125] neg_lo:[0,1] neg_hi:[0,1]
	v_mov_b32_e32 v127, v122
	v_pk_add_f32 v[122:123], v[128:129], v[126:127] neg_lo:[0,1] neg_hi:[0,1]
	s_mov_b32 s13, 0x3f317218
	v_add_f32_e32 v123, v134, v123
	v_add_f32_e32 v122, v122, v123
	v_add_f32_e32 v123, v125, v122
	v_mul_f32_e32 v134, v133, v123
	v_mul_f32_e32 v124, v131, v134
	v_fma_f32 v126, v134, v131, -v124
	v_fmac_f32_e32 v126, v134, v132
	v_sub_f32_e32 v125, v125, v123
	v_add_f32_e32 v131, v122, v125
	v_add_f32_e32 v122, v124, v126
	v_sub_f32_e32 v125, v123, v122
	v_pk_add_f32 v[128:129], v[122:123], v[124:125] neg_lo:[0,1] neg_hi:[0,1]
	v_mov_b32_e32 v127, v122
	v_pk_add_f32 v[122:123], v[128:129], v[126:127] neg_lo:[0,1] neg_hi:[0,1]
	s_nop 0
	v_add_f32_e32 v123, v131, v123
	v_add_f32_e32 v122, v122, v123
	v_add_f32_e32 v123, v135, v134
	v_add_f32_e32 v122, v125, v122
	v_sub_f32_e32 v124, v123, v135
	v_mul_f32_e32 v122, v133, v122
	v_sub_f32_e32 v124, v134, v124
	v_add_f32_e32 v124, v124, v122
	v_add_f32_e32 v126, v123, v124
	v_mul_f32_e32 v127, v126, v126
	v_mov_b32_e32 v122, 0x3ecc95a3
	v_fmamk_f32 v122, v127, 0x3e9b6dac, v122
	v_fmaak_f32 v165, v127, v122, 0x3f2aaada
	v_cvt_f32_i32_e32 v122, v130
	v_sub_f32_e32 v123, v126, v123
	v_sub_f32_e32 v123, v124, v123
	v_ldexp_f32 v128, v123, 1
	v_mul_f32_e32 v123, v126, v127
	v_ldexp_f32 v125, v126, 1
	v_pk_mul_f32 v[126:127], v[122:123], v[164:165]
	s_nop 0
	v_fma_f32 v124, v122, s13, -v126
	v_fmac_f32_e32 v124, 0xb102e308, v122
	v_pk_add_f32 v[122:123], v[126:127], v[124:125]
	s_mov_b32 s13, 0x7f800000
	v_sub_f32_e32 v125, v123, v125
	v_sub_f32_e32 v125, v127, v125
	v_add_f32_e32 v129, v128, v125
	v_mov_b32_e32 v128, v126
	v_pk_add_f32 v[126:127], v[122:123], v[126:127] neg_lo:[0,1] neg_hi:[0,1]
	v_pk_add_f32 v[130:131], v[122:123], v[128:129]
	v_mov_b32_e32 v125, v122
	v_mov_b32_e32 v127, v131
	v_pk_add_f32 v[132:133], v[124:125], v[126:127] neg_lo:[0,1] neg_hi:[0,1]
	v_pk_add_f32 v[124:125], v[124:125], v[126:127]
	v_mov_b32_e32 v128, v129
	v_pk_add_f32 v[126:127], v[124:125], v[122:123] op_sel:[1,0] op_sel_hi:[0,1] neg_lo:[0,1] neg_hi:[0,1]
	v_pk_add_f32 v[134:135], v[130:131], v[126:127] op_sel_hi:[1,0] neg_lo:[0,1] neg_hi:[0,1]
	v_mov_b32_e32 v130, v131
	v_mov_b32_e32 v131, v125
	v_pk_mov_b32 v[126:127], v[122:123], v[126:127] op_sel:[1,0]
	v_mov_b32_e32 v129, v122
	v_pk_add_f32 v[126:127], v[130:131], v[126:127] neg_lo:[0,1] neg_hi:[0,1]
	v_mov_b32_e32 v134, v132
	v_pk_add_f32 v[122:123], v[128:129], v[126:127] neg_lo:[0,1] neg_hi:[0,1]
	v_mov_b32_e32 v133, v125
	v_pk_add_f32 v[126:127], v[134:135], v[122:123]
	v_cmp_neq_f32_e32 vcc, s13, v121
	v_pk_add_f32 v[128:129], v[126:127], v[126:127] op_sel:[0,1] op_sel_hi:[1,0]
	s_mov_b32 s13, 0x33800000
	v_pk_add_f32 v[124:125], v[124:125], v[128:129] op_sel:[1,0] op_sel_hi:[0,1]
	v_mov_b32_e32 v127, v124
	v_pk_add_f32 v[130:131], v[126:127], v[132:133] neg_lo:[0,1] neg_hi:[0,1]
	v_mov_b32_e32 v123, v128
	v_sub_f32_e32 v125, v126, v130
	v_pk_add_f32 v[122:123], v[122:123], v[130:131] neg_lo:[0,1] neg_hi:[0,1]
	v_sub_f32_e32 v125, v132, v125
	v_add_f32_e32 v122, v122, v125
	v_add_f32_e32 v122, v122, v123
	v_add_f32_e32 v122, v124, v122
	v_cndmask_b32_e32 v122, v186, v122, vcc
	v_cmp_ngt_f32_e32 vcc, -1.0, v121
	s_nop 1
	v_cndmask_b32_e32 v122, v187, v122, vcc
	v_cmp_neq_f32_e32 vcc, -1.0, v121
	s_nop 1
	v_cndmask_b32_e32 v122, v188, v122, vcc
	v_cmp_lt_f32_e64 vcc, |v121|, s13
	s_nop 1
	v_cndmask_b32_e32 v121, v122, v121, vcc
	v_sub_f32_e32 v120, v120, v121
.Lpa_p1_pad:
	global_store_dword v118, v120, s[38:39]
	s_mov_b64 exec, -1
	s_mov_b32 s13, s11
	s_cmp_lt_u32 s13, 0x8200
	s_cselect_b32 s2, s13, s12
	s_add_u32 s13, s13, s21
	s_mul_i32 s2, s2, 0x1200
	s_add_u32 s2, s2, 0xe120000
	v_add_u32_e32 v37, s2, v152
	s_add_u32 s3, s2, 0x1140
	v_add_u32_e32 v155, s3, v153
	s_mov_b64 exec, s[40:41]
	global_load_dwordx4 v[20:23], v37, s[70:71]
	s_mov_b64 exec, s[42:43]
	global_load_dwordx4 v[24:27], v37, s[70:71] offset:768
	s_mov_b64 exec, -1
	global_load_dwordx4 v[28:31], v37, s[70:71] offset:1344
	global_load_dwordx4 v[32:35], v37, s[70:71] offset:2368
	s_mov_b64 exec, s[44:45]
	global_load_ushort v36, v155, s[70:71]
	s_mov_b64 exec, -1
	s_add_u32 s12, s12, s21
	s_cmp_gt_u32 s12, 0x81ff
	s_cbranch_scc1 .Lpa_done
.Lpa_loop:
	s_waitcnt vmcnt(20)
	s_mul_i32 s2, s12, 0x300
	v_add_u32_e32 v116, s2, v152
	s_lshl_b32 s2, s12, 9
	v_add_u32_e32 v117, s2, v152
	s_lshl_b32 s2, s12, 5
	v_add_u32_e32 v118, s2, v154
	s_mov_b32 s11, s13
	v_lshlrev_b32_e32 v104, 16, v84
	v_and_b32_e32 v105, 0xffff0000, v84
	v_lshlrev_b32_e32 v106, 16, v85
	v_and_b32_e32 v107, 0xffff0000, v85
	v_lshlrev_b32_e32 v108, 16, v86
	v_and_b32_e32 v109, 0xffff0000, v86
	v_lshlrev_b32_e32 v110, 16, v87
	v_and_b32_e32 v111, 0xffff0000, v87
	v_mul_f32_e32 v140, v104, v104
	v_fmac_f32_e32 v140, v105, v105
	v_fmac_f32_e32 v140, v106, v106
	v_fmac_f32_e32 v140, v107, v107
	v_fmac_f32_e32 v140, v108, v108
	v_fmac_f32_e32 v140, v109, v109
	v_fmac_f32_e32 v140, v110, v110
	v_fmac_f32_e32 v140, v111, v111
	s_nop 1
	v_add_f32_dpp v140, v140, v140 quad_perm:[1,0,3,2] row_mask:0xf bank_mask:0xf
	s_nop 1
	v_add_f32_dpp v140, v140, v140 quad_perm:[2,3,0,1] row_mask:0xf bank_mask:0xf
	s_nop 1
	v_add_f32_dpp v140, v140, v140 row_half_mirror row_mask:0xf bank_mask:0xf
	s_nop 1
	v_add_f32_dpp v140, v140, v140 row_mirror row_mask:0xf bank_mask:0xf
	s_nop 1
	v_add_f32_dpp v140, v140, v140 row_bcast:15 row_mask:0xa bank_mask:0xf
	s_nop 1
	v_add_f32_dpp v140, v140, v140 row_bcast:31 row_mask:0xc bank_mask:0xf
	s_nop 1
	v_readlane_b32 s10, v140, 63
	s_nop 3
	v_mov_b32_e32 v142, s10
	v_fmamk_f32 v142, v142, 0x3b2aaaab, v172
	v_rsq_f32_e32 v142, v142
	s_nop 0
	v_pk_mul_f32 v[104:105], v[104:105], v[142:143] op_sel_hi:[1,0]
	v_pk_mul_f32 v[106:107], v[106:107], v[142:143] op_sel_hi:[1,0]
	v_pk_mul_f32 v[108:109], v[108:109], v[142:143] op_sel_hi:[1,0]
	v_pk_mul_f32 v[110:111], v[110:111], v[142:143] op_sel_hi:[1,0]
	v_pk_mul_f32 v[104:105], v[104:105], v[48:49]
	v_pk_mul_f32 v[106:107], v[106:107], v[50:51]
	v_pk_mul_f32 v[108:109], v[108:109], v[52:53]
	v_pk_mul_f32 v[110:111], v[110:111], v[54:55]
	v_cvt_pk_bf16_f32 v148, v104, v105
	v_cvt_pk_bf16_f32 v149, v106, v107
	v_cvt_pk_bf16_f32 v150, v108, v109
	v_cvt_pk_bf16_f32 v151, v110, v111
	s_mov_b64 exec, s[40:41]
	global_store_dwordx4 v116, v[148:151], s[34:35]
	s_mov_b64 exec, -1
	v_lshlrev_b32_e32 v104, 16, v88
	v_and_b32_e32 v105, 0xffff0000, v88
	v_lshlrev_b32_e32 v106, 16, v89
	v_and_b32_e32 v107, 0xffff0000, v89
	v_lshlrev_b32_e32 v108, 16, v90
	v_and_b32_e32 v109, 0xffff0000, v90
	v_lshlrev_b32_e32 v110, 16, v91
	v_and_b32_e32 v111, 0xffff0000, v91
	v_mul_f32_e32 v140, v104, v104
	v_fmac_f32_e32 v140, v105, v105
	v_fmac_f32_e32 v140, v106, v106
	v_fmac_f32_e32 v140, v107, v107
	v_fmac_f32_e32 v140, v108, v108
	v_fmac_f32_e32 v140, v109, v109
	v_fmac_f32_e32 v140, v110, v110
	v_fmac_f32_e32 v140, v111, v111
	s_nop 1
	v_add_f32_dpp v140, v140, v140 quad_perm:[1,0,3,2] row_mask:0xf bank_mask:0xf
	s_nop 1
	v_add_f32_dpp v140, v140, v140 quad_perm:[2,3,0,1] row_mask:0xf bank_mask:0xf
	s_nop 1
	v_add_f32_dpp v140, v140, v140 row_half_mirror row_mask:0xf bank_mask:0xf
	s_nop 1
	v_add_f32_dpp v140, v140, v140 row_mirror row_mask:0xf bank_mask:0xf
	s_nop 1
	v_add_f32_dpp v140, v140, v140 row_bcast:15 row_mask:0xa bank_mask:0xf
	s_nop 1
	v_add_f32_dpp v140, v140, v140 row_bcast:31 row_mask:0xc bank_mask:0xf
	s_nop 1
	v_readlane_b32 s10, v140, 63
	s_nop 3
	v_mov_b32_e32 v142, s10
	v_fmamk_f32 v142, v142, 0x3b800000, v172
	v_rsq_f32_e32 v142, v142
	s_nop 0
	v_pk_mul_f32 v[104:105], v[104:105], v[142:143] op_sel_hi:[1,0]
	v_pk_mul_f32 v[106:107], v[106:107], v[142:143] op_sel_hi:[1,0]
	v_pk_mul_f32 v[108:109], v[108:109], v[142:143] op_sel_hi:[1,0]
	v_pk_mul_f32 v[110:111], v[110:111], v[142:143] op_sel_hi:[1,0]
	v_pk_mul_f32 v[104:105], v[104:105], v[56:57]
	v_pk_mul_f32 v[106:107], v[106:107], v[58:59]
	v_pk_mul_f32 v[108:109], v[108:109], v[60:61]
	v_pk_mul_f32 v[110:111], v[110:111], v[62:63]
	v_cvt_pk_bf16_f32 v148, v104, v105
	v_cvt_pk_bf16_f32 v149, v106, v107
	v_cvt_pk_bf16_f32 v150, v108, v109
	v_cvt_pk_bf16_f32 v151, v110, v111
	s_mov_b64 exec, s[42:43]
	global_store_dwordx4 v117, v[148:151], s[36:37]
	s_mov_b64 exec, -1
	v_lshlrev_b32_e32 v104, 16, v92
	v_and_b32_e32 v105, 0xffff0000, v92
	v_lshlrev_b32_e32 v106, 16, v93
	v_and_b32_e32 v107, 0xffff0000, v93
	v_lshlrev_b32_e32 v108, 16, v94
	v_and_b32_e32 v109, 0xffff0000, v94
	v_lshlrev_b32_e32 v110, 16, v95
	v_and_b32_e32 v111, 0xffff0000, v95
	v_mul_f32_e32 v140, v104, v104
	v_fmac_f32_e32 v140, v105, v105
	v_fmac_f32_e32 v140, v106, v106
	v_fmac_f32_e32 v140, v107, v107
	v_fmac_f32_e32 v140, v108, v108
	v_fmac_f32_e32 v140, v109, v109
	v_fmac_f32_e32 v140, v110, v110
	v_fmac_f32_e32 v140, v111, v111
	s_nop 1
	v_add_f32_dpp v140, v140, v140 quad_perm:[1,0,3,2] row_mask:0xf bank_mask:0xf
	s_nop 1
	v_add_f32_dpp v140, v140, v140 quad_perm:[2,3,0,1] row_mask:0xf bank_mask:0xf
	s_nop 1
	v_add_f32_dpp v140, v140, v140 row_half_mirror row_mask:0xf bank_mask:0xf
	v_fmamk_f32 v142, v140, 0x3c800000, v172
	v_rsq_f32_e32 v142, v142
	s_nop 0
	v_mul_f32_e32 v142, 0x3e38aa3b, v142
	v_pk_mul_f32 v[104:105], v[104:105], v[142:143] op_sel_hi:[1,0]
	v_pk_mul_f32 v[106:107], v[106:107], v[142:143] op_sel_hi:[1,0]
	v_pk_mul_f32 v[108:109], v[108:109], v[142:143] op_sel_hi:[1,0]
	v_pk_mul_f32 v[110:111], v[110:111], v[142:143] op_sel_hi:[1,0]
	v_pk_mul_f32 v[104:105], v[104:105], v[64:65]
	v_pk_mul_f32 v[106:107], v[106:107], v[66:67]
	v_pk_mul_f32 v[108:109], v[108:109], v[68:69]
	v_pk_mul_f32 v[110:111], v[110:111], v[70:71]
	v_cvt_pk_bf16_f32 v148, v104, v105
	v_cvt_pk_bf16_f32 v149, v106, v107
	v_cvt_pk_bf16_f32 v150, v108, v109
	v_cvt_pk_bf16_f32 v151, v110, v111
	global_store_dwordx4 v101, v[148:151], s[70:71] offset:1344
	v_lshlrev_b32_e32 v104, 16, v96
	v_and_b32_e32 v105, 0xffff0000, v96
	v_lshlrev_b32_e32 v106, 16, v97
	v_and_b32_e32 v107, 0xffff0000, v97
	v_lshlrev_b32_e32 v108, 16, v98
	v_and_b32_e32 v109, 0xffff0000, v98
	v_lshlrev_b32_e32 v110, 16, v99
	v_and_b32_e32 v111, 0xffff0000, v99
	v_mul_f32_e32 v140, v104, v104
	v_fmac_f32_e32 v140, v105, v105
	v_fmac_f32_e32 v140, v106, v106
	v_fmac_f32_e32 v140, v107, v107
	v_fmac_f32_e32 v140, v108, v108
	v_fmac_f32_e32 v140, v109, v109
	v_fmac_f32_e32 v140, v110, v110
	v_fmac_f32_e32 v140, v111, v111
	s_nop 1
	v_add_f32_dpp v140, v140, v140 quad_perm:[1,0,3,2] row_mask:0xf bank_mask:0xf
	s_nop 1
	v_add_f32_dpp v140, v140, v140 quad_perm:[2,3,0,1] row_mask:0xf bank_mask:0xf
	s_nop 1
	v_add_f32_dpp v140, v140, v140 row_half_mirror row_mask:0xf bank_mask:0xf
	v_fmamk_f32 v142, v140, 0x3c800000, v172
	v_rsq_f32_e32 v142, v142
	s_nop 0
	v_pk_mul_f32 v[104:105], v[104:105], v[142:143] op_sel_hi:[1,0]
	v_pk_mul_f32 v[106:107], v[106:107], v[142:143] op_sel_hi:[1,0]
	v_pk_mul_f32 v[108:109], v[108:109], v[142:143] op_sel_hi:[1,0]
	v_pk_mul_f32 v[110:111], v[110:111], v[142:143] op_sel_hi:[1,0]
	v_pk_mul_f32 v[104:105], v[104:105], v[72:73]
	v_pk_mul_f32 v[106:107], v[106:107], v[74:75]
	v_pk_mul_f32 v[108:109], v[108:109], v[76:77]
	v_pk_mul_f32 v[110:111], v[110:111], v[78:79]
	v_cvt_pk_bf16_f32 v148, v104, v105
	v_cvt_pk_bf16_f32 v149, v106, v107
	v_cvt_pk_bf16_f32 v150, v108, v109
	v_cvt_pk_bf16_f32 v151, v110, v111
	global_store_dwordx4 v101, v[148:151], s[70:71] offset:2368
	s_mul_hi_i32 s2, s12, 0x7e07e07f
	s_lshr_b32 s3, s2, 31
	s_ashr_i32 s2, s2, 12
	s_add_i32 s2, s2, s3
	s_mulk_i32 s2, 0x2080
	s_sub_i32 s2, s12, s2
	s_mov_b64 exec, s[44:45]
	v_mov_b32_e32 v120, 0
	s_cmpk_lt_i32 s2, 0x70
	s_cbranch_scc1 .Lpa_c_pad
	s_mov_b32 s13, 0xbfb8aa3b
	v_lshlrev_b32_e32 v120, 16, v100
	v_mov_b32_e32 v121, v80
	v_add_f32_e32 v121, v121, v120
	v_min_f32_e32 v120, 0, v121
	v_mul_f32_e64 v121, |v121|, s13
	v_exp_f32_e32 v121, v121
	s_mov_b32 s13, 0x3f2aaaab
	v_add_f32_e32 v124, 1.0, v121
	v_add_f32_e32 v122, -1.0, v124
	v_sub_f32_e32 v123, v122, v124
	v_add_f32_e32 v123, 1.0, v123
	v_sub_f32_e32 v122, v121, v122
	v_add_f32_e32 v125, v122, v123
	v_frexp_mant_f32_e32 v122, v124
	v_cmp_gt_f32_e32 vcc, s13, v122
	v_cvt_f64_f32_e32 v[122:123], v124
	v_frexp_exp_i32_f64_e32 v122, v[122:123]
	v_subbrev_co_u32_e32 v130, vcc, 0, v122, vcc
	v_sub_u32_e32 v122, 0, v130
	v_ldexp_f32 v123, v124, v122
	v_add_f32_e32 v124, -1.0, v123
	v_add_f32_e32 v126, 1.0, v123
	v_ldexp_f32 v122, v125, v122
	v_add_f32_e32 v125, 1.0, v124
	v_add_f32_e32 v127, -1.0, v126
	v_sub_f32_e32 v125, v123, v125
	v_sub_f32_e32 v123, v123, v127
	v_add_f32_e32 v125, v122, v125
	v_add_f32_e32 v122, v122, v123
	v_add_f32_e32 v131, v126, v122
	v_rcp_f32_e32 v133, v131
	v_sub_f32_e32 v123, v131, v126
	v_sub_f32_e32 v132, v122, v123
	v_add_f32_e32 v123, v124, v125
	v_mul_f32_e32 v135, v123, v133
	v_sub_f32_e32 v122, v123, v124
	v_mul_f32_e32 v124, v131, v135
	v_fma_f32 v126, v135, v131, -v124
	v_fmac_f32_e32 v126, v135, v132
	v_sub_f32_e32 v134, v125, v122
	v_add_f32_e32 v122, v124, v126
	v_sub_f32_e32 v125, v123, v122
	v_pk_add_f32 v[128:129], v[122:123], v[124:125] neg_lo:[0,1] neg_hi:[0,1]
	v_mov_b32_e32 v127, v122
	v_pk_add_f32 v[122:123], v[128:129], v[126:127] neg_lo:[0,1] neg_hi:[0,1]
	s_mov_b32 s13, 0x3f317218
	v_add_f32_e32 v123, v134, v123
	v_add_f32_e32 v122, v122, v123
	v_add_f32_e32 v123, v125, v122
	v_mul_f32_e32 v134, v133, v123
	v_mul_f32_e32 v124, v131, v134
	v_fma_f32 v126, v134, v131, -v124
	v_fmac_f32_e32 v126, v134, v132
	v_sub_f32_e32 v125, v125, v123
	v_add_f32_e32 v131, v122, v125
	v_add_f32_e32 v122, v124, v126
	v_sub_f32_e32 v125, v123, v122
	v_pk_add_f32 v[128:129], v[122:123], v[124:125] neg_lo:[0,1] neg_hi:[0,1]
	v_mov_b32_e32 v127, v122
	v_pk_add_f32 v[122:123], v[128:129], v[126:127] neg_lo:[0,1] neg_hi:[0,1]
	s_nop 0
	v_add_f32_e32 v123, v131, v123
	v_add_f32_e32 v122, v122, v123
	v_add_f32_e32 v123, v135, v134
	v_add_f32_e32 v122, v125, v122
	v_sub_f32_e32 v124, v123, v135
	v_mul_f32_e32 v122, v133, v122
	v_sub_f32_e32 v124, v134, v124
	v_add_f32_e32 v124, v124, v122
	v_add_f32_e32 v126, v123, v124
	v_mul_f32_e32 v127, v126, v126
	v_mov_b32_e32 v122, 0x3ecc95a3
	v_fmamk_f32 v122, v127, 0x3e9b6dac, v122
	v_fmaak_f32 v165, v127, v122, 0x3f2aaada
	v_cvt_f32_i32_e32 v122, v130
	v_sub_f32_e32 v123, v126, v123
	v_sub_f32_e32 v123, v124, v123
	v_ldexp_f32 v128, v123, 1
	v_mul_f32_e32 v123, v126, v127
	v_ldexp_f32 v125, v126, 1
	v_pk_mul_f32 v[126:127], v[122:123], v[164:165]
	s_nop 0
	v_fma_f32 v124, v122, s13, -v126
	v_fmac_f32_e32 v124, 0xb102e308, v122
	v_pk_add_f32 v[122:123], v[126:127], v[124:125]
	s_mov_b32 s13, 0x7f800000
	v_sub_f32_e32 v125, v123, v125
	v_sub_f32_e32 v125, v127, v125
	v_add_f32_e32 v129, v128, v125
	v_mov_b32_e32 v128, v126
	v_pk_add_f32 v[126:127], v[122:123], v[126:127] neg_lo:[0,1] neg_hi:[0,1]
	v_pk_add_f32 v[130:131], v[122:123], v[128:129]
	v_mov_b32_e32 v125, v122
	v_mov_b32_e32 v127, v131
	v_pk_add_f32 v[132:133], v[124:125], v[126:127] neg_lo:[0,1] neg_hi:[0,1]
	v_pk_add_f32 v[124:125], v[124:125], v[126:127]
	v_mov_b32_e32 v128, v129
	v_pk_add_f32 v[126:127], v[124:125], v[122:123] op_sel:[1,0] op_sel_hi:[0,1] neg_lo:[0,1] neg_hi:[0,1]
	v_pk_add_f32 v[134:135], v[130:131], v[126:127] op_sel_hi:[1,0] neg_lo:[0,1] neg_hi:[0,1]
	v_mov_b32_e32 v130, v131
	v_mov_b32_e32 v131, v125
	v_pk_mov_b32 v[126:127], v[122:123], v[126:127] op_sel:[1,0]
	v_mov_b32_e32 v129, v122
	v_pk_add_f32 v[126:127], v[130:131], v[126:127] neg_lo:[0,1] neg_hi:[0,1]
	v_mov_b32_e32 v134, v132
	v_pk_add_f32 v[122:123], v[128:129], v[126:127] neg_lo:[0,1] neg_hi:[0,1]
	v_mov_b32_e32 v133, v125
	v_pk_add_f32 v[126:127], v[134:135], v[122:123]
	v_cmp_neq_f32_e32 vcc, s13, v121
	v_pk_add_f32 v[128:129], v[126:127], v[126:127] op_sel:[0,1] op_sel_hi:[1,0]
	s_mov_b32 s13, 0x33800000
	v_pk_add_f32 v[124:125], v[124:125], v[128:129] op_sel:[1,0] op_sel_hi:[0,1]
	v_mov_b32_e32 v127, v124
	v_pk_add_f32 v[130:131], v[126:127], v[132:133] neg_lo:[0,1] neg_hi:[0,1]
	v_mov_b32_e32 v123, v128
	v_sub_f32_e32 v125, v126, v130
	v_pk_add_f32 v[122:123], v[122:123], v[130:131] neg_lo:[0,1] neg_hi:[0,1]
	v_sub_f32_e32 v125, v132, v125
	v_add_f32_e32 v122, v122, v125
	v_add_f32_e32 v122, v122, v123
	v_add_f32_e32 v122, v124, v122
	v_cndmask_b32_e32 v122, v186, v122, vcc
	v_cmp_ngt_f32_e32 vcc, -1.0, v121
	s_nop 1
	v_cndmask_b32_e32 v122, v187, v122, vcc
	v_cmp_neq_f32_e32 vcc, -1.0, v121
	s_nop 1
	v_cndmask_b32_e32 v122, v188, v122, vcc
	v_cmp_lt_f32_e64 vcc, |v121|, s13
	s_nop 1
	v_cndmask_b32_e32 v121, v122, v121, vcc
	v_sub_f32_e32 v120, v120, v121
.Lpa_c_pad:
	global_store_dword v118, v120, s[38:39]
	s_mov_b64 exec, -1
	s_mov_b32 s13, s11
	s_cmp_lt_u32 s13, 0x8200
	s_cselect_b32 s2, s13, s12
	s_add_u32 s13, s13, s21
	s_mul_i32 s2, s2, 0x1200
	s_add_u32 s2, s2, 0xe120000
	v_add_u32_e32 v101, s2, v152
	s_add_u32 s3, s2, 0x1140
	v_add_u32_e32 v155, s3, v153
	s_mov_b64 exec, s[40:41]
	global_load_dwordx4 v[84:87], v101, s[70:71]
	s_mov_b64 exec, s[42:43]
	global_load_dwordx4 v[88:91], v101, s[70:71] offset:768
	s_mov_b64 exec, -1
	global_load_dwordx4 v[92:95], v101, s[70:71] offset:1344
	global_load_dwordx4 v[96:99], v101, s[70:71] offset:2368
	s_mov_b64 exec, s[44:45]
	global_load_ushort v100, v155, s[70:71]
	s_mov_b64 exec, -1
	s_add_u32 s12, s12, s21
	s_cmp_gt_u32 s12, 0x81ff
	s_cbranch_scc1 .Lpa_done
	s_waitcnt vmcnt(20)
	s_mul_i32 s2, s12, 0x300
	v_add_u32_e32 v116, s2, v152
	s_lshl_b32 s2, s12, 9
	v_add_u32_e32 v117, s2, v152
	s_lshl_b32 s2, s12, 5
	v_add_u32_e32 v118, s2, v154
	s_mov_b32 s11, s13
	v_lshlrev_b32_e32 v104, 16, v0
	v_and_b32_e32 v105, 0xffff0000, v0
	v_lshlrev_b32_e32 v106, 16, v1
	v_and_b32_e32 v107, 0xffff0000, v1
	v_lshlrev_b32_e32 v108, 16, v2
	v_and_b32_e32 v109, 0xffff0000, v2
	v_lshlrev_b32_e32 v110, 16, v3
	v_and_b32_e32 v111, 0xffff0000, v3
	v_mul_f32_e32 v140, v104, v104
	v_fmac_f32_e32 v140, v105, v105
	v_fmac_f32_e32 v140, v106, v106
	v_fmac_f32_e32 v140, v107, v107
	v_fmac_f32_e32 v140, v108, v108
	v_fmac_f32_e32 v140, v109, v109
	v_fmac_f32_e32 v140, v110, v110
	v_fmac_f32_e32 v140, v111, v111
	s_nop 1
	v_add_f32_dpp v140, v140, v140 quad_perm:[1,0,3,2] row_mask:0xf bank_mask:0xf
	s_nop 1
	v_add_f32_dpp v140, v140, v140 quad_perm:[2,3,0,1] row_mask:0xf bank_mask:0xf
	s_nop 1
	v_add_f32_dpp v140, v140, v140 row_half_mirror row_mask:0xf bank_mask:0xf
	s_nop 1
	v_add_f32_dpp v140, v140, v140 row_mirror row_mask:0xf bank_mask:0xf
	s_nop 1
	v_add_f32_dpp v140, v140, v140 row_bcast:15 row_mask:0xa bank_mask:0xf
	s_nop 1
	v_add_f32_dpp v140, v140, v140 row_bcast:31 row_mask:0xc bank_mask:0xf
	s_nop 1
	v_readlane_b32 s10, v140, 63
	s_nop 3
	v_mov_b32_e32 v142, s10
	v_fmamk_f32 v142, v142, 0x3b2aaaab, v172
	v_rsq_f32_e32 v142, v142
	s_nop 0
	v_pk_mul_f32 v[104:105], v[104:105], v[142:143] op_sel_hi:[1,0]
	v_pk_mul_f32 v[106:107], v[106:107], v[142:143] op_sel_hi:[1,0]
	v_pk_mul_f32 v[108:109], v[108:109], v[142:143] op_sel_hi:[1,0]
	v_pk_mul_f32 v[110:111], v[110:111], v[142:143] op_sel_hi:[1,0]
	v_pk_mul_f32 v[104:105], v[104:105], v[48:49]
	v_pk_mul_f32 v[106:107], v[106:107], v[50:51]
	v_pk_mul_f32 v[108:109], v[108:109], v[52:53]
	v_pk_mul_f32 v[110:111], v[110:111], v[54:55]
	v_cvt_pk_bf16_f32 v148, v104, v105
	v_cvt_pk_bf16_f32 v149, v106, v107
	v_cvt_pk_bf16_f32 v150, v108, v109
	v_cvt_pk_bf16_f32 v151, v110, v111
	s_mov_b64 exec, s[40:41]
	global_store_dwordx4 v116, v[148:151], s[34:35]
	s_mov_b64 exec, -1
	v_lshlrev_b32_e32 v104, 16, v4
	v_and_b32_e32 v105, 0xffff0000, v4
	v_lshlrev_b32_e32 v106, 16, v5
	v_and_b32_e32 v107, 0xffff0000, v5
	v_lshlrev_b32_e32 v108, 16, v6
	v_and_b32_e32 v109, 0xffff0000, v6
	v_lshlrev_b32_e32 v110, 16, v7
	v_and_b32_e32 v111, 0xffff0000, v7
	v_mul_f32_e32 v140, v104, v104
	v_fmac_f32_e32 v140, v105, v105
	v_fmac_f32_e32 v140, v106, v106
	v_fmac_f32_e32 v140, v107, v107
	v_fmac_f32_e32 v140, v108, v108
	v_fmac_f32_e32 v140, v109, v109
	v_fmac_f32_e32 v140, v110, v110
	v_fmac_f32_e32 v140, v111, v111
	s_nop 1
	v_add_f32_dpp v140, v140, v140 quad_perm:[1,0,3,2] row_mask:0xf bank_mask:0xf
	s_nop 1
	v_add_f32_dpp v140, v140, v140 quad_perm:[2,3,0,1] row_mask:0xf bank_mask:0xf
	s_nop 1
	v_add_f32_dpp v140, v140, v140 row_half_mirror row_mask:0xf bank_mask:0xf
	s_nop 1
	v_add_f32_dpp v140, v140, v140 row_mirror row_mask:0xf bank_mask:0xf
	s_nop 1
	v_add_f32_dpp v140, v140, v140 row_bcast:15 row_mask:0xa bank_mask:0xf
	s_nop 1
	v_add_f32_dpp v140, v140, v140 row_bcast:31 row_mask:0xc bank_mask:0xf
	s_nop 1
	v_readlane_b32 s10, v140, 63
	s_nop 3
	v_mov_b32_e32 v142, s10
	v_fmamk_f32 v142, v142, 0x3b800000, v172
	v_rsq_f32_e32 v142, v142
	s_nop 0
	v_pk_mul_f32 v[104:105], v[104:105], v[142:143] op_sel_hi:[1,0]
	v_pk_mul_f32 v[106:107], v[106:107], v[142:143] op_sel_hi:[1,0]
	v_pk_mul_f32 v[108:109], v[108:109], v[142:143] op_sel_hi:[1,0]
	v_pk_mul_f32 v[110:111], v[110:111], v[142:143] op_sel_hi:[1,0]
	v_pk_mul_f32 v[104:105], v[104:105], v[56:57]
	v_pk_mul_f32 v[106:107], v[106:107], v[58:59]
	v_pk_mul_f32 v[108:109], v[108:109], v[60:61]
	v_pk_mul_f32 v[110:111], v[110:111], v[62:63]
	v_cvt_pk_bf16_f32 v148, v104, v105
	v_cvt_pk_bf16_f32 v149, v106, v107
	v_cvt_pk_bf16_f32 v150, v108, v109
	v_cvt_pk_bf16_f32 v151, v110, v111
	s_mov_b64 exec, s[42:43]
	global_store_dwordx4 v117, v[148:151], s[36:37]
	s_mov_b64 exec, -1
	v_lshlrev_b32_e32 v104, 16, v8
	v_and_b32_e32 v105, 0xffff0000, v8
	v_lshlrev_b32_e32 v106, 16, v9
	v_and_b32_e32 v107, 0xffff0000, v9
	v_lshlrev_b32_e32 v108, 16, v10
	v_and_b32_e32 v109, 0xffff0000, v10
	v_lshlrev_b32_e32 v110, 16, v11
	v_and_b32_e32 v111, 0xffff0000, v11
	v_mul_f32_e32 v140, v104, v104
	v_fmac_f32_e32 v140, v105, v105
	v_fmac_f32_e32 v140, v106, v106
	v_fmac_f32_e32 v140, v107, v107
	v_fmac_f32_e32 v140, v108, v108
	v_fmac_f32_e32 v140, v109, v109
	v_fmac_f32_e32 v140, v110, v110
	v_fmac_f32_e32 v140, v111, v111
	s_nop 1
	v_add_f32_dpp v140, v140, v140 quad_perm:[1,0,3,2] row_mask:0xf bank_mask:0xf
	s_nop 1
	v_add_f32_dpp v140, v140, v140 quad_perm:[2,3,0,1] row_mask:0xf bank_mask:0xf
	s_nop 1
	v_add_f32_dpp v140, v140, v140 row_half_mirror row_mask:0xf bank_mask:0xf
	v_fmamk_f32 v142, v140, 0x3c800000, v172
	v_rsq_f32_e32 v142, v142
	s_nop 0
	v_mul_f32_e32 v142, 0x3e38aa3b, v142
	v_pk_mul_f32 v[104:105], v[104:105], v[142:143] op_sel_hi:[1,0]
	v_pk_mul_f32 v[106:107], v[106:107], v[142:143] op_sel_hi:[1,0]
	v_pk_mul_f32 v[108:109], v[108:109], v[142:143] op_sel_hi:[1,0]
	v_pk_mul_f32 v[110:111], v[110:111], v[142:143] op_sel_hi:[1,0]
	v_pk_mul_f32 v[104:105], v[104:105], v[64:65]
	v_pk_mul_f32 v[106:107], v[106:107], v[66:67]
	v_pk_mul_f32 v[108:109], v[108:109], v[68:69]
	v_pk_mul_f32 v[110:111], v[110:111], v[70:71]
	v_cvt_pk_bf16_f32 v148, v104, v105
	v_cvt_pk_bf16_f32 v149, v106, v107
	v_cvt_pk_bf16_f32 v150, v108, v109
	v_cvt_pk_bf16_f32 v151, v110, v111
	global_store_dwordx4 v17, v[148:151], s[70:71] offset:1344
	v_lshlrev_b32_e32 v104, 16, v12
	v_and_b32_e32 v105, 0xffff0000, v12
	v_lshlrev_b32_e32 v106, 16, v13
	v_and_b32_e32 v107, 0xffff0000, v13
	v_lshlrev_b32_e32 v108, 16, v14
	v_and_b32_e32 v109, 0xffff0000, v14
	v_lshlrev_b32_e32 v110, 16, v15
	v_and_b32_e32 v111, 0xffff0000, v15
	v_mul_f32_e32 v140, v104, v104
	v_fmac_f32_e32 v140, v105, v105
	v_fmac_f32_e32 v140, v106, v106
	v_fmac_f32_e32 v140, v107, v107
	v_fmac_f32_e32 v140, v108, v108
	v_fmac_f32_e32 v140, v109, v109
	v_fmac_f32_e32 v140, v110, v110
	v_fmac_f32_e32 v140, v111, v111
	s_nop 1
	v_add_f32_dpp v140, v140, v140 quad_perm:[1,0,3,2] row_mask:0xf bank_mask:0xf
	s_nop 1
	v_add_f32_dpp v140, v140, v140 quad_perm:[2,3,0,1] row_mask:0xf bank_mask:0xf
	s_nop 1
	v_add_f32_dpp v140, v140, v140 row_half_mirror row_mask:0xf bank_mask:0xf
	v_fmamk_f32 v142, v140, 0x3c800000, v172
	v_rsq_f32_e32 v142, v142
	s_nop 0
	v_pk_mul_f32 v[104:105], v[104:105], v[142:143] op_sel_hi:[1,0]
	v_pk_mul_f32 v[106:107], v[106:107], v[142:143] op_sel_hi:[1,0]
	v_pk_mul_f32 v[108:109], v[108:109], v[142:143] op_sel_hi:[1,0]
	v_pk_mul_f32 v[110:111], v[110:111], v[142:143] op_sel_hi:[1,0]
	v_pk_mul_f32 v[104:105], v[104:105], v[72:73]
	v_pk_mul_f32 v[106:107], v[106:107], v[74:75]
	v_pk_mul_f32 v[108:109], v[108:109], v[76:77]
	v_pk_mul_f32 v[110:111], v[110:111], v[78:79]
	v_cvt_pk_bf16_f32 v148, v104, v105
	v_cvt_pk_bf16_f32 v149, v106, v107
	v_cvt_pk_bf16_f32 v150, v108, v109
	v_cvt_pk_bf16_f32 v151, v110, v111
	global_store_dwordx4 v17, v[148:151], s[70:71] offset:2368
	s_mul_hi_i32 s2, s12, 0x7e07e07f
	s_lshr_b32 s3, s2, 31
	s_ashr_i32 s2, s2, 12
	s_add_i32 s2, s2, s3
	s_mulk_i32 s2, 0x2080
	s_sub_i32 s2, s12, s2
	s_mov_b64 exec, s[44:45]
	v_mov_b32_e32 v120, 0
	s_cmpk_lt_i32 s2, 0x70
	s_cbranch_scc1 .Lpa_a_pad
	s_mov_b32 s13, 0xbfb8aa3b
	v_lshlrev_b32_e32 v120, 16, v16
	v_mov_b32_e32 v121, v80
	v_add_f32_e32 v121, v121, v120
	v_min_f32_e32 v120, 0, v121
	v_mul_f32_e64 v121, |v121|, s13
	v_exp_f32_e32 v121, v121
	s_mov_b32 s13, 0x3f2aaaab
	v_add_f32_e32 v124, 1.0, v121
	v_add_f32_e32 v122, -1.0, v124
	v_sub_f32_e32 v123, v122, v124
	v_add_f32_e32 v123, 1.0, v123
	v_sub_f32_e32 v122, v121, v122
	v_add_f32_e32 v125, v122, v123
	v_frexp_mant_f32_e32 v122, v124
	v_cmp_gt_f32_e32 vcc, s13, v122
	v_cvt_f64_f32_e32 v[122:123], v124
	v_frexp_exp_i32_f64_e32 v122, v[122:123]
	v_subbrev_co_u32_e32 v130, vcc, 0, v122, vcc
	v_sub_u32_e32 v122, 0, v130
	v_ldexp_f32 v123, v124, v122
	v_add_f32_e32 v124, -1.0, v123
	v_add_f32_e32 v126, 1.0, v123
	v_ldexp_f32 v122, v125, v122
	v_add_f32_e32 v125, 1.0, v124
	v_add_f32_e32 v127, -1.0, v126
	v_sub_f32_e32 v125, v123, v125
	v_sub_f32_e32 v123, v123, v127
	v_add_f32_e32 v125, v122, v125
	v_add_f32_e32 v122, v122, v123
	v_add_f32_e32 v131, v126, v122
	v_rcp_f32_e32 v133, v131
	v_sub_f32_e32 v123, v131, v126
	v_sub_f32_e32 v132, v122, v123
	v_add_f32_e32 v123, v124, v125
	v_mul_f32_e32 v135, v123, v133
	v_sub_f32_e32 v122, v123, v124
	v_mul_f32_e32 v124, v131, v135
	v_fma_f32 v126, v135, v131, -v124
	v_fmac_f32_e32 v126, v135, v132
	v_sub_f32_e32 v134, v125, v122
	v_add_f32_e32 v122, v124, v126
	v_sub_f32_e32 v125, v123, v122
	v_pk_add_f32 v[128:129], v[122:123], v[124:125] neg_lo:[0,1] neg_hi:[0,1]
	v_mov_b32_e32 v127, v122
	v_pk_add_f32 v[122:123], v[128:129], v[126:127] neg_lo:[0,1] neg_hi:[0,1]
	s_mov_b32 s13, 0x3f317218
	v_add_f32_e32 v123, v134, v123
	v_add_f32_e32 v122, v122, v123
	v_add_f32_e32 v123, v125, v122
	v_mul_f32_e32 v134, v133, v123
	v_mul_f32_e32 v124, v131, v134
	v_fma_f32 v126, v134, v131, -v124
	v_fmac_f32_e32 v126, v134, v132
	v_sub_f32_e32 v125, v125, v123
	v_add_f32_e32 v131, v122, v125
	v_add_f32_e32 v122, v124, v126
	v_sub_f32_e32 v125, v123, v122
	v_pk_add_f32 v[128:129], v[122:123], v[124:125] neg_lo:[0,1] neg_hi:[0,1]
	v_mov_b32_e32 v127, v122
	v_pk_add_f32 v[122:123], v[128:129], v[126:127] neg_lo:[0,1] neg_hi:[0,1]
	s_nop 0
	v_add_f32_e32 v123, v131, v123
	v_add_f32_e32 v122, v122, v123
	v_add_f32_e32 v123, v135, v134
	v_add_f32_e32 v122, v125, v122
	v_sub_f32_e32 v124, v123, v135
	v_mul_f32_e32 v122, v133, v122
	v_sub_f32_e32 v124, v134, v124
	v_add_f32_e32 v124, v124, v122
	v_add_f32_e32 v126, v123, v124
	v_mul_f32_e32 v127, v126, v126
	v_mov_b32_e32 v122, 0x3ecc95a3
	v_fmamk_f32 v122, v127, 0x3e9b6dac, v122
	v_fmaak_f32 v165, v127, v122, 0x3f2aaada
	v_cvt_f32_i32_e32 v122, v130
	v_sub_f32_e32 v123, v126, v123
	v_sub_f32_e32 v123, v124, v123
	v_ldexp_f32 v128, v123, 1
	v_mul_f32_e32 v123, v126, v127
	v_ldexp_f32 v125, v126, 1
	v_pk_mul_f32 v[126:127], v[122:123], v[164:165]
	s_nop 0
	v_fma_f32 v124, v122, s13, -v126
	v_fmac_f32_e32 v124, 0xb102e308, v122
	v_pk_add_f32 v[122:123], v[126:127], v[124:125]
	s_mov_b32 s13, 0x7f800000
	v_sub_f32_e32 v125, v123, v125
	v_sub_f32_e32 v125, v127, v125
	v_add_f32_e32 v129, v128, v125
	v_mov_b32_e32 v128, v126
	v_pk_add_f32 v[126:127], v[122:123], v[126:127] neg_lo:[0,1] neg_hi:[0,1]
	v_pk_add_f32 v[130:131], v[122:123], v[128:129]
	v_mov_b32_e32 v125, v122
	v_mov_b32_e32 v127, v131
	v_pk_add_f32 v[132:133], v[124:125], v[126:127] neg_lo:[0,1] neg_hi:[0,1]
	v_pk_add_f32 v[124:125], v[124:125], v[126:127]
	v_mov_b32_e32 v128, v129
	v_pk_add_f32 v[126:127], v[124:125], v[122:123] op_sel:[1,0] op_sel_hi:[0,1] neg_lo:[0,1] neg_hi:[0,1]
	v_pk_add_f32 v[134:135], v[130:131], v[126:127] op_sel_hi:[1,0] neg_lo:[0,1] neg_hi:[0,1]
	v_mov_b32_e32 v130, v131
	v_mov_b32_e32 v131, v125
	v_pk_mov_b32 v[126:127], v[122:123], v[126:127] op_sel:[1,0]
	v_mov_b32_e32 v129, v122
	v_pk_add_f32 v[126:127], v[130:131], v[126:127] neg_lo:[0,1] neg_hi:[0,1]
	v_mov_b32_e32 v134, v132
	v_pk_add_f32 v[122:123], v[128:129], v[126:127] neg_lo:[0,1] neg_hi:[0,1]
	v_mov_b32_e32 v133, v125
	v_pk_add_f32 v[126:127], v[134:135], v[122:123]
	v_cmp_neq_f32_e32 vcc, s13, v121
	v_pk_add_f32 v[128:129], v[126:127], v[126:127] op_sel:[0,1] op_sel_hi:[1,0]
	s_mov_b32 s13, 0x33800000
	v_pk_add_f32 v[124:125], v[124:125], v[128:129] op_sel:[1,0] op_sel_hi:[0,1]
	v_mov_b32_e32 v127, v124
	v_pk_add_f32 v[130:131], v[126:127], v[132:133] neg_lo:[0,1] neg_hi:[0,1]
	v_mov_b32_e32 v123, v128
	v_sub_f32_e32 v125, v126, v130
	v_pk_add_f32 v[122:123], v[122:123], v[130:131] neg_lo:[0,1] neg_hi:[0,1]
	v_sub_f32_e32 v125, v132, v125
	v_add_f32_e32 v122, v122, v125
	v_add_f32_e32 v122, v122, v123
	v_add_f32_e32 v122, v124, v122
	v_cndmask_b32_e32 v122, v186, v122, vcc
	v_cmp_ngt_f32_e32 vcc, -1.0, v121
	s_nop 1
	v_cndmask_b32_e32 v122, v187, v122, vcc
	v_cmp_neq_f32_e32 vcc, -1.0, v121
	s_nop 1
	v_cndmask_b32_e32 v122, v188, v122, vcc
	v_cmp_lt_f32_e64 vcc, |v121|, s13
	s_nop 1
	v_cndmask_b32_e32 v121, v122, v121, vcc
	v_sub_f32_e32 v120, v120, v121
.Lpa_a_pad:
	global_store_dword v118, v120, s[38:39]
	s_mov_b64 exec, -1
	s_mov_b32 s13, s11
	s_cmp_lt_u32 s13, 0x8200
	s_cselect_b32 s2, s13, s12
	s_add_u32 s13, s13, s21
	s_mul_i32 s2, s2, 0x1200
	s_add_u32 s2, s2, 0xe120000
	v_add_u32_e32 v17, s2, v152
	s_add_u32 s3, s2, 0x1140
	v_add_u32_e32 v155, s3, v153
	s_mov_b64 exec, s[40:41]
	global_load_dwordx4 v[0:3], v17, s[70:71]
	s_mov_b64 exec, s[42:43]
	global_load_dwordx4 v[4:7], v17, s[70:71] offset:768
	s_mov_b64 exec, -1
	global_load_dwordx4 v[8:11], v17, s[70:71] offset:1344
	global_load_dwordx4 v[12:15], v17, s[70:71] offset:2368
	s_mov_b64 exec, s[44:45]
	global_load_ushort v16, v155, s[70:71]
	s_mov_b64 exec, -1
	s_add_u32 s12, s12, s21
	s_cmp_gt_u32 s12, 0x81ff
	s_cbranch_scc1 .Lpa_done
	s_waitcnt vmcnt(20)
	s_mul_i32 s2, s12, 0x300
	v_add_u32_e32 v116, s2, v152
	s_lshl_b32 s2, s12, 9
	v_add_u32_e32 v117, s2, v152
	s_lshl_b32 s2, s12, 5
	v_add_u32_e32 v118, s2, v154
	s_mov_b32 s11, s13
	v_lshlrev_b32_e32 v104, 16, v20
	v_and_b32_e32 v105, 0xffff0000, v20
	v_lshlrev_b32_e32 v106, 16, v21
	v_and_b32_e32 v107, 0xffff0000, v21
	v_lshlrev_b32_e32 v108, 16, v22
	v_and_b32_e32 v109, 0xffff0000, v22
	v_lshlrev_b32_e32 v110, 16, v23
	v_and_b32_e32 v111, 0xffff0000, v23
	v_mul_f32_e32 v140, v104, v104
	v_fmac_f32_e32 v140, v105, v105
	v_fmac_f32_e32 v140, v106, v106
	v_fmac_f32_e32 v140, v107, v107
	v_fmac_f32_e32 v140, v108, v108
	v_fmac_f32_e32 v140, v109, v109
	v_fmac_f32_e32 v140, v110, v110
	v_fmac_f32_e32 v140, v111, v111
	s_nop 1
	v_add_f32_dpp v140, v140, v140 quad_perm:[1,0,3,2] row_mask:0xf bank_mask:0xf
	s_nop 1
	v_add_f32_dpp v140, v140, v140 quad_perm:[2,3,0,1] row_mask:0xf bank_mask:0xf
	s_nop 1
	v_add_f32_dpp v140, v140, v140 row_half_mirror row_mask:0xf bank_mask:0xf
	s_nop 1
	v_add_f32_dpp v140, v140, v140 row_mirror row_mask:0xf bank_mask:0xf
	s_nop 1
	v_add_f32_dpp v140, v140, v140 row_bcast:15 row_mask:0xa bank_mask:0xf
	s_nop 1
	v_add_f32_dpp v140, v140, v140 row_bcast:31 row_mask:0xc bank_mask:0xf
	s_nop 1
	v_readlane_b32 s10, v140, 63
	s_nop 3
	v_mov_b32_e32 v142, s10
	v_fmamk_f32 v142, v142, 0x3b2aaaab, v172
	v_rsq_f32_e32 v142, v142
	s_nop 0
	v_pk_mul_f32 v[104:105], v[104:105], v[142:143] op_sel_hi:[1,0]
	v_pk_mul_f32 v[106:107], v[106:107], v[142:143] op_sel_hi:[1,0]
	v_pk_mul_f32 v[108:109], v[108:109], v[142:143] op_sel_hi:[1,0]
	v_pk_mul_f32 v[110:111], v[110:111], v[142:143] op_sel_hi:[1,0]
	v_pk_mul_f32 v[104:105], v[104:105], v[48:49]
	v_pk_mul_f32 v[106:107], v[106:107], v[50:51]
	v_pk_mul_f32 v[108:109], v[108:109], v[52:53]
	v_pk_mul_f32 v[110:111], v[110:111], v[54:55]
	v_cvt_pk_bf16_f32 v148, v104, v105
	v_cvt_pk_bf16_f32 v149, v106, v107
	v_cvt_pk_bf16_f32 v150, v108, v109
	v_cvt_pk_bf16_f32 v151, v110, v111
	s_mov_b64 exec, s[40:41]
	global_store_dwordx4 v116, v[148:151], s[34:35]
	s_mov_b64 exec, -1
	v_lshlrev_b32_e32 v104, 16, v24
	v_and_b32_e32 v105, 0xffff0000, v24
	v_lshlrev_b32_e32 v106, 16, v25
	v_and_b32_e32 v107, 0xffff0000, v25
	v_lshlrev_b32_e32 v108, 16, v26
	v_and_b32_e32 v109, 0xffff0000, v26
	v_lshlrev_b32_e32 v110, 16, v27
	v_and_b32_e32 v111, 0xffff0000, v27
	v_mul_f32_e32 v140, v104, v104
	v_fmac_f32_e32 v140, v105, v105
	v_fmac_f32_e32 v140, v106, v106
	v_fmac_f32_e32 v140, v107, v107
	v_fmac_f32_e32 v140, v108, v108
	v_fmac_f32_e32 v140, v109, v109
	v_fmac_f32_e32 v140, v110, v110
	v_fmac_f32_e32 v140, v111, v111
	s_nop 1
	v_add_f32_dpp v140, v140, v140 quad_perm:[1,0,3,2] row_mask:0xf bank_mask:0xf
	s_nop 1
	v_add_f32_dpp v140, v140, v140 quad_perm:[2,3,0,1] row_mask:0xf bank_mask:0xf
	s_nop 1
	v_add_f32_dpp v140, v140, v140 row_half_mirror row_mask:0xf bank_mask:0xf
	s_nop 1
	v_add_f32_dpp v140, v140, v140 row_mirror row_mask:0xf bank_mask:0xf
	s_nop 1
	v_add_f32_dpp v140, v140, v140 row_bcast:15 row_mask:0xa bank_mask:0xf
	s_nop 1
	v_add_f32_dpp v140, v140, v140 row_bcast:31 row_mask:0xc bank_mask:0xf
	s_nop 1
	v_readlane_b32 s10, v140, 63
	s_nop 3
	v_mov_b32_e32 v142, s10
	v_fmamk_f32 v142, v142, 0x3b800000, v172
	v_rsq_f32_e32 v142, v142
	s_nop 0
	v_pk_mul_f32 v[104:105], v[104:105], v[142:143] op_sel_hi:[1,0]
	v_pk_mul_f32 v[106:107], v[106:107], v[142:143] op_sel_hi:[1,0]
	v_pk_mul_f32 v[108:109], v[108:109], v[142:143] op_sel_hi:[1,0]
	v_pk_mul_f32 v[110:111], v[110:111], v[142:143] op_sel_hi:[1,0]
	v_pk_mul_f32 v[104:105], v[104:105], v[56:57]
	v_pk_mul_f32 v[106:107], v[106:107], v[58:59]
	v_pk_mul_f32 v[108:109], v[108:109], v[60:61]
	v_pk_mul_f32 v[110:111], v[110:111], v[62:63]
	v_cvt_pk_bf16_f32 v148, v104, v105
	v_cvt_pk_bf16_f32 v149, v106, v107
	v_cvt_pk_bf16_f32 v150, v108, v109
	v_cvt_pk_bf16_f32 v151, v110, v111
	s_mov_b64 exec, s[42:43]
	global_store_dwordx4 v117, v[148:151], s[36:37]
	s_mov_b64 exec, -1
	v_lshlrev_b32_e32 v104, 16, v28
	v_and_b32_e32 v105, 0xffff0000, v28
	v_lshlrev_b32_e32 v106, 16, v29
	v_and_b32_e32 v107, 0xffff0000, v29
	v_lshlrev_b32_e32 v108, 16, v30
	v_and_b32_e32 v109, 0xffff0000, v30
	v_lshlrev_b32_e32 v110, 16, v31
	v_and_b32_e32 v111, 0xffff0000, v31
	v_mul_f32_e32 v140, v104, v104
	v_fmac_f32_e32 v140, v105, v105
	v_fmac_f32_e32 v140, v106, v106
	v_fmac_f32_e32 v140, v107, v107
	v_fmac_f32_e32 v140, v108, v108
	v_fmac_f32_e32 v140, v109, v109
	v_fmac_f32_e32 v140, v110, v110
	v_fmac_f32_e32 v140, v111, v111
	s_nop 1
	v_add_f32_dpp v140, v140, v140 quad_perm:[1,0,3,2] row_mask:0xf bank_mask:0xf
	s_nop 1
	v_add_f32_dpp v140, v140, v140 quad_perm:[2,3,0,1] row_mask:0xf bank_mask:0xf
	s_nop 1
	v_add_f32_dpp v140, v140, v140 row_half_mirror row_mask:0xf bank_mask:0xf
	v_fmamk_f32 v142, v140, 0x3c800000, v172
	v_rsq_f32_e32 v142, v142
	s_nop 0
	v_mul_f32_e32 v142, 0x3e38aa3b, v142
	v_pk_mul_f32 v[104:105], v[104:105], v[142:143] op_sel_hi:[1,0]
	v_pk_mul_f32 v[106:107], v[106:107], v[142:143] op_sel_hi:[1,0]
	v_pk_mul_f32 v[108:109], v[108:109], v[142:143] op_sel_hi:[1,0]
	v_pk_mul_f32 v[110:111], v[110:111], v[142:143] op_sel_hi:[1,0]
	v_pk_mul_f32 v[104:105], v[104:105], v[64:65]
	v_pk_mul_f32 v[106:107], v[106:107], v[66:67]
	v_pk_mul_f32 v[108:109], v[108:109], v[68:69]
	v_pk_mul_f32 v[110:111], v[110:111], v[70:71]
	v_cvt_pk_bf16_f32 v148, v104, v105
	v_cvt_pk_bf16_f32 v149, v106, v107
	v_cvt_pk_bf16_f32 v150, v108, v109
	v_cvt_pk_bf16_f32 v151, v110, v111
	global_store_dwordx4 v37, v[148:151], s[70:71] offset:1344
	v_lshlrev_b32_e32 v104, 16, v32
	v_and_b32_e32 v105, 0xffff0000, v32
	v_lshlrev_b32_e32 v106, 16, v33
	v_and_b32_e32 v107, 0xffff0000, v33
	v_lshlrev_b32_e32 v108, 16, v34
	v_and_b32_e32 v109, 0xffff0000, v34
	v_lshlrev_b32_e32 v110, 16, v35
	v_and_b32_e32 v111, 0xffff0000, v35
	v_mul_f32_e32 v140, v104, v104
	v_fmac_f32_e32 v140, v105, v105
	v_fmac_f32_e32 v140, v106, v106
	v_fmac_f32_e32 v140, v107, v107
	v_fmac_f32_e32 v140, v108, v108
	v_fmac_f32_e32 v140, v109, v109
	v_fmac_f32_e32 v140, v110, v110
	v_fmac_f32_e32 v140, v111, v111
	s_nop 1
	v_add_f32_dpp v140, v140, v140 quad_perm:[1,0,3,2] row_mask:0xf bank_mask:0xf
	s_nop 1
	v_add_f32_dpp v140, v140, v140 quad_perm:[2,3,0,1] row_mask:0xf bank_mask:0xf
	s_nop 1
	v_add_f32_dpp v140, v140, v140 row_half_mirror row_mask:0xf bank_mask:0xf
	v_fmamk_f32 v142, v140, 0x3c800000, v172
	v_rsq_f32_e32 v142, v142
	s_nop 0
	v_pk_mul_f32 v[104:105], v[104:105], v[142:143] op_sel_hi:[1,0]
	v_pk_mul_f32 v[106:107], v[106:107], v[142:143] op_sel_hi:[1,0]
	v_pk_mul_f32 v[108:109], v[108:109], v[142:143] op_sel_hi:[1,0]
	v_pk_mul_f32 v[110:111], v[110:111], v[142:143] op_sel_hi:[1,0]
	v_pk_mul_f32 v[104:105], v[104:105], v[72:73]
	v_pk_mul_f32 v[106:107], v[106:107], v[74:75]
	v_pk_mul_f32 v[108:109], v[108:109], v[76:77]
	v_pk_mul_f32 v[110:111], v[110:111], v[78:79]
	v_cvt_pk_bf16_f32 v148, v104, v105
	v_cvt_pk_bf16_f32 v149, v106, v107
	v_cvt_pk_bf16_f32 v150, v108, v109
	v_cvt_pk_bf16_f32 v151, v110, v111
	global_store_dwordx4 v37, v[148:151], s[70:71] offset:2368
	s_mul_hi_i32 s2, s12, 0x7e07e07f
	s_lshr_b32 s3, s2, 31
	s_ashr_i32 s2, s2, 12
	s_add_i32 s2, s2, s3
	s_mulk_i32 s2, 0x2080
	s_sub_i32 s2, s12, s2
	s_mov_b64 exec, s[44:45]
	v_mov_b32_e32 v120, 0
	s_cmpk_lt_i32 s2, 0x70
	s_cbranch_scc1 .Lpa_b_pad
	s_mov_b32 s13, 0xbfb8aa3b
	v_lshlrev_b32_e32 v120, 16, v36
	v_mov_b32_e32 v121, v80
	v_add_f32_e32 v121, v121, v120
	v_min_f32_e32 v120, 0, v121
	v_mul_f32_e64 v121, |v121|, s13
	v_exp_f32_e32 v121, v121
	s_mov_b32 s13, 0x3f2aaaab
	v_add_f32_e32 v124, 1.0, v121
	v_add_f32_e32 v122, -1.0, v124
	v_sub_f32_e32 v123, v122, v124
	v_add_f32_e32 v123, 1.0, v123
	v_sub_f32_e32 v122, v121, v122
	v_add_f32_e32 v125, v122, v123
	v_frexp_mant_f32_e32 v122, v124
	v_cmp_gt_f32_e32 vcc, s13, v122
	v_cvt_f64_f32_e32 v[122:123], v124
	v_frexp_exp_i32_f64_e32 v122, v[122:123]
	v_subbrev_co_u32_e32 v130, vcc, 0, v122, vcc
	v_sub_u32_e32 v122, 0, v130
	v_ldexp_f32 v123, v124, v122
	v_add_f32_e32 v124, -1.0, v123
	v_add_f32_e32 v126, 1.0, v123
	v_ldexp_f32 v122, v125, v122
	v_add_f32_e32 v125, 1.0, v124
	v_add_f32_e32 v127, -1.0, v126
	v_sub_f32_e32 v125, v123, v125
	v_sub_f32_e32 v123, v123, v127
	v_add_f32_e32 v125, v122, v125
	v_add_f32_e32 v122, v122, v123
	v_add_f32_e32 v131, v126, v122
	v_rcp_f32_e32 v133, v131
	v_sub_f32_e32 v123, v131, v126
	v_sub_f32_e32 v132, v122, v123
	v_add_f32_e32 v123, v124, v125
	v_mul_f32_e32 v135, v123, v133
	v_sub_f32_e32 v122, v123, v124
	v_mul_f32_e32 v124, v131, v135
	v_fma_f32 v126, v135, v131, -v124
	v_fmac_f32_e32 v126, v135, v132
	v_sub_f32_e32 v134, v125, v122
	v_add_f32_e32 v122, v124, v126
	v_sub_f32_e32 v125, v123, v122
	v_pk_add_f32 v[128:129], v[122:123], v[124:125] neg_lo:[0,1] neg_hi:[0,1]
	v_mov_b32_e32 v127, v122
	v_pk_add_f32 v[122:123], v[128:129], v[126:127] neg_lo:[0,1] neg_hi:[0,1]
	s_mov_b32 s13, 0x3f317218
	v_add_f32_e32 v123, v134, v123
	v_add_f32_e32 v122, v122, v123
	v_add_f32_e32 v123, v125, v122
	v_mul_f32_e32 v134, v133, v123
	v_mul_f32_e32 v124, v131, v134
	v_fma_f32 v126, v134, v131, -v124
	v_fmac_f32_e32 v126, v134, v132
	v_sub_f32_e32 v125, v125, v123
	v_add_f32_e32 v131, v122, v125
	v_add_f32_e32 v122, v124, v126
	v_sub_f32_e32 v125, v123, v122
	v_pk_add_f32 v[128:129], v[122:123], v[124:125] neg_lo:[0,1] neg_hi:[0,1]
	v_mov_b32_e32 v127, v122
	v_pk_add_f32 v[122:123], v[128:129], v[126:127] neg_lo:[0,1] neg_hi:[0,1]
	s_nop 0
	v_add_f32_e32 v123, v131, v123
	v_add_f32_e32 v122, v122, v123
	v_add_f32_e32 v123, v135, v134
	v_add_f32_e32 v122, v125, v122
	v_sub_f32_e32 v124, v123, v135
	v_mul_f32_e32 v122, v133, v122
	v_sub_f32_e32 v124, v134, v124
	v_add_f32_e32 v124, v124, v122
	v_add_f32_e32 v126, v123, v124
	v_mul_f32_e32 v127, v126, v126
	v_mov_b32_e32 v122, 0x3ecc95a3
	v_fmamk_f32 v122, v127, 0x3e9b6dac, v122
	v_fmaak_f32 v165, v127, v122, 0x3f2aaada
	v_cvt_f32_i32_e32 v122, v130
	v_sub_f32_e32 v123, v126, v123
	v_sub_f32_e32 v123, v124, v123
	v_ldexp_f32 v128, v123, 1
	v_mul_f32_e32 v123, v126, v127
	v_ldexp_f32 v125, v126, 1
	v_pk_mul_f32 v[126:127], v[122:123], v[164:165]
	s_nop 0
	v_fma_f32 v124, v122, s13, -v126
	v_fmac_f32_e32 v124, 0xb102e308, v122
	v_pk_add_f32 v[122:123], v[126:127], v[124:125]
	s_mov_b32 s13, 0x7f800000
	v_sub_f32_e32 v125, v123, v125
	v_sub_f32_e32 v125, v127, v125
	v_add_f32_e32 v129, v128, v125
	v_mov_b32_e32 v128, v126
	v_pk_add_f32 v[126:127], v[122:123], v[126:127] neg_lo:[0,1] neg_hi:[0,1]
	v_pk_add_f32 v[130:131], v[122:123], v[128:129]
	v_mov_b32_e32 v125, v122
	v_mov_b32_e32 v127, v131
	v_pk_add_f32 v[132:133], v[124:125], v[126:127] neg_lo:[0,1] neg_hi:[0,1]
	v_pk_add_f32 v[124:125], v[124:125], v[126:127]
	v_mov_b32_e32 v128, v129
	v_pk_add_f32 v[126:127], v[124:125], v[122:123] op_sel:[1,0] op_sel_hi:[0,1] neg_lo:[0,1] neg_hi:[0,1]
	v_pk_add_f32 v[134:135], v[130:131], v[126:127] op_sel_hi:[1,0] neg_lo:[0,1] neg_hi:[0,1]
	v_mov_b32_e32 v130, v131
	v_mov_b32_e32 v131, v125
	v_pk_mov_b32 v[126:127], v[122:123], v[126:127] op_sel:[1,0]
	v_mov_b32_e32 v129, v122
	v_pk_add_f32 v[126:127], v[130:131], v[126:127] neg_lo:[0,1] neg_hi:[0,1]
	v_mov_b32_e32 v134, v132
	v_pk_add_f32 v[122:123], v[128:129], v[126:127] neg_lo:[0,1] neg_hi:[0,1]
	v_mov_b32_e32 v133, v125
	v_pk_add_f32 v[126:127], v[134:135], v[122:123]
	v_cmp_neq_f32_e32 vcc, s13, v121
	v_pk_add_f32 v[128:129], v[126:127], v[126:127] op_sel:[0,1] op_sel_hi:[1,0]
	s_mov_b32 s13, 0x33800000
	v_pk_add_f32 v[124:125], v[124:125], v[128:129] op_sel:[1,0] op_sel_hi:[0,1]
	v_mov_b32_e32 v127, v124
	v_pk_add_f32 v[130:131], v[126:127], v[132:133] neg_lo:[0,1] neg_hi:[0,1]
	v_mov_b32_e32 v123, v128
	v_sub_f32_e32 v125, v126, v130
	v_pk_add_f32 v[122:123], v[122:123], v[130:131] neg_lo:[0,1] neg_hi:[0,1]
	v_sub_f32_e32 v125, v132, v125
	v_add_f32_e32 v122, v122, v125
	v_add_f32_e32 v122, v122, v123
	v_add_f32_e32 v122, v124, v122
	v_cndmask_b32_e32 v122, v186, v122, vcc
	v_cmp_ngt_f32_e32 vcc, -1.0, v121
	s_nop 1
	v_cndmask_b32_e32 v122, v187, v122, vcc
	v_cmp_neq_f32_e32 vcc, -1.0, v121
	s_nop 1
	v_cndmask_b32_e32 v122, v188, v122, vcc
	v_cmp_lt_f32_e64 vcc, |v121|, s13
	s_nop 1
	v_cndmask_b32_e32 v121, v122, v121, vcc
	v_sub_f32_e32 v120, v120, v121
.Lpa_b_pad:
	global_store_dword v118, v120, s[38:39]
	s_mov_b64 exec, -1
	s_mov_b32 s13, s11
	s_cmp_lt_u32 s13, 0x8200
	s_cselect_b32 s2, s13, s12
	s_add_u32 s13, s13, s21
	s_mul_i32 s2, s2, 0x1200
	s_add_u32 s2, s2, 0xe120000
	v_add_u32_e32 v37, s2, v152
	s_add_u32 s3, s2, 0x1140
	v_add_u32_e32 v155, s3, v153
	s_mov_b64 exec, s[40:41]
	global_load_dwordx4 v[20:23], v37, s[70:71]
	s_mov_b64 exec, s[42:43]
	global_load_dwordx4 v[24:27], v37, s[70:71] offset:768
	s_mov_b64 exec, -1
	global_load_dwordx4 v[28:31], v37, s[70:71] offset:1344
	global_load_dwordx4 v[32:35], v37, s[70:71] offset:2368
	s_mov_b64 exec, s[44:45]
	global_load_ushort v36, v155, s[70:71]
	s_mov_b64 exec, -1
	s_add_u32 s12, s12, s21
	s_cmp_gt_u32 s12, 0x81ff
	s_cbranch_scc1 .Lpa_done
	s_branch .Lpa_loop
.Lpa_done:
	s_waitcnt vmcnt(0)
.LBB0_443:
	v_readlane_b32 s4, v253, 40
	v_readlane_b32 s5, v253, 41

.LBB0_445:
	s_andn2_b64 vcc, exec, s[0:1]
	s_cbranch_vccnz .LBB0_450
	s_cmpk_gt_i32 s20, 0x1ff
	s_cbranch_scc1 .LBB0_450
	s_waitcnt lgkmcnt(0)
	v_readlane_b32 s34, v251, 49
	v_readlane_b32 s35, v251, 50
	v_lshlrev_b32_e32 v130, 4, v189
	s_mov_b32 s12, s4
	s_add_i32 s21, s20, 0x8000
.Lfin_loop:
	s_lshl_b32 s2, s21, 12
	v_add_u32_e32 v132, s2, v130
	global_load_dwordx4 v[0:3], v132, s[72:73]
	global_load_dwordx4 v[4:7], v132, s[72:73] offset:1024
	global_load_dwordx4 v[8:11], v132, s[72:73] offset:2048
	global_load_dwordx4 v[12:15], v132, s[72:73] offset:3072
	s_lshl_b32 s3, s20, 12
	v_add_u32_e32 v151, s3, v130
	s_mov_b32 s3, 0x200000
	global_load_dwordx4 v[64:67], v151, s[34:35]
	global_load_dwordx4 v[68:71], v151, s[34:35] offset:1024
	global_load_dwordx4 v[72:75], v151, s[34:35] offset:2048
	global_load_dwordx4 v[76:79], v151, s[34:35] offset:3072
	v_add_u32_e32 v151, s3, v151
	global_load_dwordx4 v[80:83], v151, s[34:35]
	global_load_dwordx4 v[84:87], v151, s[34:35] offset:1024
	global_load_dwordx4 v[88:91], v151, s[34:35] offset:2048
	global_load_dwordx4 v[92:95], v151, s[34:35] offset:3072
	v_add_u32_e32 v151, s3, v151
	global_load_dwordx4 v[96:99], v151, s[34:35]
	global_load_dwordx4 v[100:103], v151, s[34:35] offset:1024
	global_load_dwordx4 v[104:107], v151, s[34:35] offset:2048
	global_load_dwordx4 v[108:111], v151, s[34:35] offset:3072
	v_add_u32_e32 v151, s3, v151
	global_load_dwordx4 v[114:117], v151, s[34:35]
	global_load_dwordx4 v[118:121], v151, s[34:35] offset:1024
	global_load_dwordx4 v[122:125], v151, s[34:35] offset:2048
	global_load_dwordx4 v[126:129], v151, s[34:35] offset:3072
	v_add_u32_e32 v151, s3, v151
	global_load_dwordx4 v[16:19], v151, s[34:35]
	global_load_dwordx4 v[20:23], v151, s[34:35] offset:1024
	global_load_dwordx4 v[24:27], v151, s[34:35] offset:2048
	global_load_dwordx4 v[28:31], v151, s[34:35] offset:3072
	v_add_u32_e32 v151, s3, v151
	global_load_dwordx4 v[32:35], v151, s[34:35]
	global_load_dwordx4 v[36:39], v151, s[34:35] offset:1024
	global_load_dwordx4 v[40:43], v151, s[34:35] offset:2048
	global_load_dwordx4 v[44:47], v151, s[34:35] offset:3072
	v_add_u32_e32 v151, s3, v151
	global_load_dwordx4 v[192:195], v151, s[34:35]
	global_load_dwordx4 v[196:199], v151, s[34:35] offset:1024
	global_load_dwordx4 v[200:203], v151, s[34:35] offset:2048
	global_load_dwordx4 v[204:207], v151, s[34:35] offset:3072
	v_add_u32_e32 v151, s3, v151
	global_load_dwordx4 v[208:211], v151, s[34:35]
	global_load_dwordx4 v[212:215], v151, s[34:35] offset:1024
	global_load_dwordx4 v[216:219], v151, s[34:35] offset:2048
	global_load_dwordx4 v[220:223], v151, s[34:35] offset:3072
	s_waitcnt vmcnt(28)
	v_pk_add_f32 v[0:1], v[0:1], v[64:65]
	v_pk_add_f32 v[2:3], v[2:3], v[66:67]
	v_pk_add_f32 v[4:5], v[4:5], v[68:69]
	v_pk_add_f32 v[6:7], v[6:7], v[70:71]
	v_pk_add_f32 v[8:9], v[8:9], v[72:73]
	v_pk_add_f32 v[10:11], v[10:11], v[74:75]
	v_pk_add_f32 v[12:13], v[12:13], v[76:77]
	v_pk_add_f32 v[14:15], v[14:15], v[78:79]
	s_waitcnt vmcnt(24)
	v_pk_add_f32 v[0:1], v[0:1], v[80:81]
	v_pk_add_f32 v[2:3], v[2:3], v[82:83]
	v_pk_add_f32 v[4:5], v[4:5], v[84:85]
	v_pk_add_f32 v[6:7], v[6:7], v[86:87]
	v_pk_add_f32 v[8:9], v[8:9], v[88:89]
	v_pk_add_f32 v[10:11], v[10:11], v[90:91]
	v_pk_add_f32 v[12:13], v[12:13], v[92:93]
	v_pk_add_f32 v[14:15], v[14:15], v[94:95]
	s_waitcnt vmcnt(20)
	v_pk_add_f32 v[0:1], v[0:1], v[96:97]
	v_pk_add_f32 v[2:3], v[2:3], v[98:99]
	v_pk_add_f32 v[4:5], v[4:5], v[100:101]
	v_pk_add_f32 v[6:7], v[6:7], v[102:103]
	v_pk_add_f32 v[8:9], v[8:9], v[104:105]
	v_pk_add_f32 v[10:11], v[10:11], v[106:107]
	v_pk_add_f32 v[12:13], v[12:13], v[108:109]
	v_pk_add_f32 v[14:15], v[14:15], v[110:111]
	s_waitcnt vmcnt(16)
	v_pk_add_f32 v[0:1], v[0:1], v[114:115]
	v_pk_add_f32 v[2:3], v[2:3], v[116:117]
	v_pk_add_f32 v[4:5], v[4:5], v[118:119]
	v_pk_add_f32 v[6:7], v[6:7], v[120:121]
	v_pk_add_f32 v[8:9], v[8:9], v[122:123]
	v_pk_add_f32 v[10:11], v[10:11], v[124:125]
	v_pk_add_f32 v[12:13], v[12:13], v[126:127]
	v_pk_add_f32 v[14:15], v[14:15], v[128:129]
	s_waitcnt vmcnt(12)
	v_pk_add_f32 v[0:1], v[0:1], v[16:17]
	v_pk_add_f32 v[2:3], v[2:3], v[18:19]
	v_pk_add_f32 v[4:5], v[4:5], v[20:21]
	v_pk_add_f32 v[6:7], v[6:7], v[22:23]
	v_pk_add_f32 v[8:9], v[8:9], v[24:25]
	v_pk_add_f32 v[10:11], v[10:11], v[26:27]
	v_pk_add_f32 v[12:13], v[12:13], v[28:29]
	v_pk_add_f32 v[14:15], v[14:15], v[30:31]
	s_waitcnt vmcnt(8)
	v_pk_add_f32 v[0:1], v[0:1], v[32:33]
	v_pk_add_f32 v[2:3], v[2:3], v[34:35]
	v_pk_add_f32 v[4:5], v[4:5], v[36:37]
	v_pk_add_f32 v[6:7], v[6:7], v[38:39]
	v_pk_add_f32 v[8:9], v[8:9], v[40:41]
	v_pk_add_f32 v[10:11], v[10:11], v[42:43]
	v_pk_add_f32 v[12:13], v[12:13], v[44:45]
	v_pk_add_f32 v[14:15], v[14:15], v[46:47]
	s_waitcnt vmcnt(4)
	v_pk_add_f32 v[0:1], v[0:1], v[192:193]
	v_pk_add_f32 v[2:3], v[2:3], v[194:195]
	v_pk_add_f32 v[4:5], v[4:5], v[196:197]
	v_pk_add_f32 v[6:7], v[6:7], v[198:199]
	v_pk_add_f32 v[8:9], v[8:9], v[200:201]
	v_pk_add_f32 v[10:11], v[10:11], v[202:203]
	v_pk_add_f32 v[12:13], v[12:13], v[204:205]
	v_pk_add_f32 v[14:15], v[14:15], v[206:207]
	s_waitcnt vmcnt(0)
	v_pk_add_f32 v[0:1], v[0:1], v[208:209]
	v_pk_add_f32 v[2:3], v[2:3], v[210:211]
	v_pk_add_f32 v[4:5], v[4:5], v[212:213]
	v_pk_add_f32 v[6:7], v[6:7], v[214:215]
	v_pk_add_f32 v[8:9], v[8:9], v[216:217]
	v_pk_add_f32 v[10:11], v[10:11], v[218:219]
	v_pk_add_f32 v[12:13], v[12:13], v[220:221]
	v_pk_add_f32 v[14:15], v[14:15], v[222:223]
	s_sub_u32 s2, s21, 0x200
	s_lshl_b32 s2, s2, 12
	v_add_u32_e32 v132, s2, v130
	global_store_dwordx4 v132, v[0:3], s[68:69]
	global_store_dwordx4 v132, v[4:7], s[68:69] offset:1024
	global_store_dwordx4 v132, v[8:11], s[68:69] offset:2048
	global_store_dwordx4 v132, v[12:15], s[68:69] offset:3072
	s_add_u32 s20, s20, s12
	s_add_u32 s21, s21, s12
	s_cmp_gt_i32 s21, 0x81ff
	s_cbranch_scc0 .Lfin_loop
	s_mov_b32 s4, s12

.LBB0_638:
	s_lshr_b32 s4, s14, 3
	s_and_b32 s3, s13, 7
	s_mul_i32 s4, s4, 0x10400
	s_mov_b32 s5, s80
	s_lshl_b32 s3, s3, 2
	s_lshl_b64 s[4:5], s[4:5], 2
	s_or_b32 s4, s4, s3
	v_lshl_add_u64 v[6:7], v[2:3], 0, s[4:5]
	v_mov_b32_e32 v1, 0
	v_mov_b32_e32 v192, 0
	v_mov_b32_e32 v193, 0
	v_mov_b32_e32 v194, 0
	v_mov_b32_e32 v195, 0
	v_mov_b32_e32 v196, 0
	v_mov_b32_e32 v197, 0
	v_mov_b32_e32 v198, 0
	v_mov_b32_e32 v199, 0
	v_mov_b32_e32 v200, 0
	v_mov_b32_e32 v201, 0
	v_mov_b32_e32 v202, 0
	v_mov_b32_e32 v203, 0
	v_mov_b32_e32 v204, 0
	v_mov_b32_e32 v205, 0
	v_mov_b32_e32 v206, 0
	v_mov_b32_e32 v207, 0
	v_mov_b32_e32 v208, 0
	s_mov_b64 s[4:5], exec
	v_add_u32_e32 v17, 0, v0
	v_cmp_lt_i32_e32 vcc, v17, v10
	s_and_b64 exec, vcc, s[4:5]
	global_load_dword v192, v[6:7], off
	v_add_u32_e32 v17, 1, v0
	v_cmp_lt_i32_e32 vcc, v17, v10
	s_and_b64 exec, vcc, s[4:5]
	global_load_dword v193, v[6:7], off offset:32
	v_add_u32_e32 v17, 2, v0
	v_cmp_lt_i32_e32 vcc, v17, v10
	s_and_b64 exec, vcc, s[4:5]
	global_load_dword v194, v[6:7], off offset:64
	v_add_u32_e32 v17, 3, v0
	v_cmp_lt_i32_e32 vcc, v17, v10
	s_and_b64 exec, vcc, s[4:5]
	global_load_dword v195, v[6:7], off offset:96
	v_add_u32_e32 v17, 4, v0
	v_cmp_lt_i32_e32 vcc, v17, v10
	s_and_b64 exec, vcc, s[4:5]
	global_load_dword v196, v[6:7], off offset:128
	v_add_u32_e32 v17, 5, v0
	v_cmp_lt_i32_e32 vcc, v17, v10
	s_and_b64 exec, vcc, s[4:5]
	global_load_dword v197, v[6:7], off offset:160
	v_add_u32_e32 v17, 6, v0
	v_cmp_lt_i32_e32 vcc, v17, v10
	s_and_b64 exec, vcc, s[4:5]
	global_load_dword v198, v[6:7], off offset:192
	v_add_u32_e32 v17, 7, v0
	v_cmp_lt_i32_e32 vcc, v17, v10
	s_and_b64 exec, vcc, s[4:5]
	global_load_dword v199, v[6:7], off offset:224
	v_add_u32_e32 v17, 8, v0
	v_cmp_lt_i32_e32 vcc, v17, v10
	s_and_b64 exec, vcc, s[4:5]
	global_load_dword v200, v[6:7], off offset:256
	v_add_u32_e32 v17, 9, v0
	v_cmp_lt_i32_e32 vcc, v17, v10
	s_and_b64 exec, vcc, s[4:5]
	global_load_dword v201, v[6:7], off offset:288
	v_add_u32_e32 v17, 10, v0
	v_cmp_lt_i32_e32 vcc, v17, v10
	s_and_b64 exec, vcc, s[4:5]
	global_load_dword v202, v[6:7], off offset:320
	v_add_u32_e32 v17, 11, v0
	v_cmp_lt_i32_e32 vcc, v17, v10
	s_and_b64 exec, vcc, s[4:5]
	global_load_dword v203, v[6:7], off offset:352
	v_add_u32_e32 v17, 12, v0
	v_cmp_lt_i32_e32 vcc, v17, v10
	s_and_b64 exec, vcc, s[4:5]
	global_load_dword v204, v[6:7], off offset:384
	v_add_u32_e32 v17, 13, v0
	v_cmp_lt_i32_e32 vcc, v17, v10
	s_and_b64 exec, vcc, s[4:5]
	global_load_dword v205, v[6:7], off offset:416
	v_add_u32_e32 v17, 14, v0
	v_cmp_lt_i32_e32 vcc, v17, v10
	s_and_b64 exec, vcc, s[4:5]
	global_load_dword v206, v[6:7], off offset:448
	v_add_u32_e32 v17, 15, v0
	v_cmp_lt_i32_e32 vcc, v17, v10
	s_and_b64 exec, vcc, s[4:5]
	global_load_dword v207, v[6:7], off offset:480
	v_add_u32_e32 v17, 16, v0
	v_cmp_lt_i32_e32 vcc, v17, v10
	s_and_b64 exec, vcc, s[4:5]
	global_load_dword v208, v[6:7], off offset:512
	s_mov_b64 exec, s[4:5]
	s_waitcnt vmcnt(0)
	v_add_f32_e32 v1, v1, v192
	v_add_f32_e32 v1, v1, v193
	v_add_f32_e32 v1, v1, v194
	v_add_f32_e32 v1, v1, v195
	v_add_f32_e32 v1, v1, v196
	v_add_f32_e32 v1, v1, v197
	v_add_f32_e32 v1, v1, v198
	v_add_f32_e32 v1, v1, v199
	v_add_f32_e32 v1, v1, v200
	v_add_f32_e32 v1, v1, v201
	v_add_f32_e32 v1, v1, v202
	v_add_f32_e32 v1, v1, v203
	v_add_f32_e32 v1, v1, v204
	v_add_f32_e32 v1, v1, v205
	v_add_f32_e32 v1, v1, v206
	v_add_f32_e32 v1, v1, v207
	v_add_f32_e32 v1, v1, v208

.LBB0_649:
	v_cndmask_b32_e64 v18, v9, v8, s[50:51]
	s_mov_b32 s3, s80
	v_add_f32_e32 v17, v18, v17
	v_lshl_add_u64 v[8:9], s[2:3], 2, v[4:5]
	v_sub_f32_e32 v1, v17, v1
	v_add_f32_e32 v1, v1, v192
	v_mul_f32_e32 v209, 0x3fb8aa3b, v1
	v_add_f32_e32 v1, v1, v193
	v_mul_f32_e32 v210, 0x3fb8aa3b, v1
	v_add_f32_e32 v1, v1, v194
	v_mul_f32_e32 v211, 0x3fb8aa3b, v1
	v_add_f32_e32 v1, v1, v195
	v_mul_f32_e32 v212, 0x3fb8aa3b, v1
	v_add_f32_e32 v1, v1, v196
	v_mul_f32_e32 v213, 0x3fb8aa3b, v1
	v_add_f32_e32 v1, v1, v197
	v_mul_f32_e32 v214, 0x3fb8aa3b, v1
	v_add_f32_e32 v1, v1, v198
	v_mul_f32_e32 v215, 0x3fb8aa3b, v1
	v_add_f32_e32 v1, v1, v199
	v_mul_f32_e32 v216, 0x3fb8aa3b, v1
	v_add_f32_e32 v1, v1, v200
	v_mul_f32_e32 v217, 0x3fb8aa3b, v1
	v_add_f32_e32 v1, v1, v201
	v_mul_f32_e32 v218, 0x3fb8aa3b, v1
	v_add_f32_e32 v1, v1, v202
	v_mul_f32_e32 v219, 0x3fb8aa3b, v1
	v_add_f32_e32 v1, v1, v203
	v_mul_f32_e32 v220, 0x3fb8aa3b, v1
	v_add_f32_e32 v1, v1, v204
	v_mul_f32_e32 v221, 0x3fb8aa3b, v1
	v_add_f32_e32 v1, v1, v205
	v_mul_f32_e32 v222, 0x3fb8aa3b, v1
	v_add_f32_e32 v1, v1, v206
	v_mul_f32_e32 v223, 0x3fb8aa3b, v1
	v_add_f32_e32 v1, v1, v207
	v_mul_f32_e32 v224, 0x3fb8aa3b, v1
	v_add_f32_e32 v1, v1, v208
	v_mul_f32_e32 v225, 0x3fb8aa3b, v1
	v_add_u32_e32 v17, 0, v0
	v_cmp_lt_i32_e32 vcc, v17, v10
	s_and_b64 exec, vcc, s[4:5]
	global_store_dword v[8:9], v209, off
	v_add_u32_e32 v17, 1, v0
	v_cmp_lt_i32_e32 vcc, v17, v10
	s_and_b64 exec, vcc, s[4:5]
	global_store_dword v[8:9], v210, off offset:4
	v_add_u32_e32 v17, 2, v0
	v_cmp_lt_i32_e32 vcc, v17, v10
	s_and_b64 exec, vcc, s[4:5]
	global_store_dword v[8:9], v211, off offset:8
	v_add_u32_e32 v17, 3, v0
	v_cmp_lt_i32_e32 vcc, v17, v10
	s_and_b64 exec, vcc, s[4:5]
	global_store_dword v[8:9], v212, off offset:12
	v_add_u32_e32 v17, 4, v0
	v_cmp_lt_i32_e32 vcc, v17, v10
	s_and_b64 exec, vcc, s[4:5]
	global_store_dword v[8:9], v213, off offset:16
	v_add_u32_e32 v17, 5, v0
	v_cmp_lt_i32_e32 vcc, v17, v10
	s_and_b64 exec, vcc, s[4:5]
	global_store_dword v[8:9], v214, off offset:20
	v_add_u32_e32 v17, 6, v0
	v_cmp_lt_i32_e32 vcc, v17, v10
	s_and_b64 exec, vcc, s[4:5]
	global_store_dword v[8:9], v215, off offset:24
	v_add_u32_e32 v17, 7, v0
	v_cmp_lt_i32_e32 vcc, v17, v10
	s_and_b64 exec, vcc, s[4:5]
	global_store_dword v[8:9], v216, off offset:28
	v_add_u32_e32 v17, 8, v0
	v_cmp_lt_i32_e32 vcc, v17, v10
	s_and_b64 exec, vcc, s[4:5]
	global_store_dword v[8:9], v217, off offset:32
	v_add_u32_e32 v17, 9, v0
	v_cmp_lt_i32_e32 vcc, v17, v10
	s_and_b64 exec, vcc, s[4:5]
	global_store_dword v[8:9], v218, off offset:36
	v_add_u32_e32 v17, 10, v0
	v_cmp_lt_i32_e32 vcc, v17, v10
	s_and_b64 exec, vcc, s[4:5]
	global_store_dword v[8:9], v219, off offset:40
	v_add_u32_e32 v17, 11, v0
	v_cmp_lt_i32_e32 vcc, v17, v10
	s_and_b64 exec, vcc, s[4:5]
	global_store_dword v[8:9], v220, off offset:44
	v_add_u32_e32 v17, 12, v0
	v_cmp_lt_i32_e32 vcc, v17, v10
	s_and_b64 exec, vcc, s[4:5]
	global_store_dword v[8:9], v221, off offset:48
	v_add_u32_e32 v17, 13, v0
	v_cmp_lt_i32_e32 vcc, v17, v10
	s_and_b64 exec, vcc, s[4:5]
	global_store_dword v[8:9], v222, off offset:52
	v_add_u32_e32 v17, 14, v0
	v_cmp_lt_i32_e32 vcc, v17, v10
	s_and_b64 exec, vcc, s[4:5]
	global_store_dword v[8:9], v223, off offset:56
	v_add_u32_e32 v17, 15, v0
	v_cmp_lt_i32_e32 vcc, v17, v10
	s_and_b64 exec, vcc, s[4:5]
	global_store_dword v[8:9], v224, off offset:60
	v_add_u32_e32 v17, 16, v0
	v_cmp_lt_i32_e32 vcc, v17, v10
	s_and_b64 exec, vcc, s[4:5]
	global_store_dword v[8:9], v225, off offset:64
	s_branch .LBB0_637

.LBB0_680:
	v_lshl_add_u32 v112, s53, 8, v146
	v_ashrrev_i32_e32 v144, 31, v112
	v_mul_lo_u32 v150, s6, v144
	v_mul_lo_u32 v151, s7, v112
	v_mad_u64_u32 v[144:145], s[20:21], s6, v112, 0
	v_lshl_or_b32 v114, s52, 8, v148
	v_add3_u32 v145, v145, v150, v151
	v_ashrrev_i32_e32 v115, 31, v114
	v_lshl_add_u64 v[144:145], v[144:145], 1, s[24:25]
	v_lshl_add_u64 v[144:145], v[114:115], 1, v[144:145]
	v_cvt_pk_bf16_f32 v128, v128, v129
	v_cvt_pk_bf16_f32 v129, v130, v131
	v_cvt_pk_bf16_f32 v130, v124, v125
	v_cvt_pk_bf16_f32 v131, v126, v127
	s_and_b64 vcc, exec, s[38:39]
	global_store_dwordx4 v[144:145], v[128:131], off
	s_cbranch_vccnz .LBB0_682
	v_max_f32_e32 v121, 0, v121
	v_max_f32_e32 v120, 0, v120
	v_max_f32_e32 v123, 0, v123
	v_max_f32_e32 v122, 0, v122
	v_max_f32_e32 v117, 0, v117
	v_max_f32_e32 v116, 0, v116
	v_max_f32_e32 v119, 0, v119
	v_max_f32_e32 v118, 0, v118
	v_pk_mul_f32 v[122:123], v[122:123], v[122:123]
	v_pk_mul_f32 v[120:121], v[120:121], v[120:121]
	v_pk_mul_f32 v[118:119], v[118:119], v[118:119]
	v_pk_mul_f32 v[116:117], v[116:117], v[116:117]
.LBB0_682:
	v_cvt_pk_bf16_f32 v120, v120, v121
	v_cvt_pk_bf16_f32 v121, v122, v123
	v_cvt_pk_bf16_f32 v122, v116, v117
	v_cvt_pk_bf16_f32 v123, v118, v119
	s_and_b64 vcc, exec, s[38:39]
	global_store_dwordx4 v[144:145], v[120:123], off offset:256
	s_cbranch_vccnz .LBB0_684
	v_max_f32_e32 v109, 0, v109
	v_max_f32_e32 v108, 0, v108
	v_max_f32_e32 v111, 0, v111
	v_max_f32_e32 v110, 0, v110
	v_max_f32_e32 v105, 0, v105
	v_max_f32_e32 v104, 0, v104
	v_max_f32_e32 v107, 0, v107
	v_max_f32_e32 v106, 0, v106
	v_pk_mul_f32 v[110:111], v[110:111], v[110:111]
	v_pk_mul_f32 v[108:109], v[108:109], v[108:109]
	v_pk_mul_f32 v[106:107], v[106:107], v[106:107]
	v_pk_mul_f32 v[104:105], v[104:105], v[104:105]
.LBB0_684:
	v_or_b32_e32 v116, 16, v112
	v_mul_lo_u32 v118, s7, v116
	v_mad_u64_u32 v[116:117], s[20:21], s6, v116, 0
	v_add3_u32 v117, v117, v150, v118
	v_lshl_add_u64 v[116:117], v[116:117], 1, s[24:25]
	v_lshl_add_u64 v[116:117], v[114:115], 1, v[116:117]
	v_cvt_pk_bf16_f32 v108, v108, v109
	v_cvt_pk_bf16_f32 v109, v110, v111
	v_cvt_pk_bf16_f32 v110, v104, v105
	v_cvt_pk_bf16_f32 v111, v106, v107
	s_and_b64 vcc, exec, s[38:39]
	global_store_dwordx4 v[116:117], v[108:111], off
	s_cbranch_vccnz .LBB0_686
	v_max_f32_e32 v101, 0, v101
	v_max_f32_e32 v100, 0, v100
	v_max_f32_e32 v103, 0, v103
	v_max_f32_e32 v102, 0, v102
	v_max_f32_e32 v97, 0, v97
	v_max_f32_e32 v96, 0, v96
	v_max_f32_e32 v99, 0, v99
	v_max_f32_e32 v98, 0, v98
	v_pk_mul_f32 v[102:103], v[102:103], v[102:103]
	v_pk_mul_f32 v[100:101], v[100:101], v[100:101]
	v_pk_mul_f32 v[98:99], v[98:99], v[98:99]
	v_pk_mul_f32 v[96:97], v[96:97], v[96:97]
.LBB0_686:
	v_cvt_pk_bf16_f32 v100, v100, v101
	v_cvt_pk_bf16_f32 v101, v102, v103
	v_cvt_pk_bf16_f32 v102, v96, v97
	v_cvt_pk_bf16_f32 v103, v98, v99
	s_and_b64 vcc, exec, s[38:39]
	global_store_dwordx4 v[116:117], v[100:103], off offset:256
	s_cbranch_vccnz .LBB0_688
	v_max_f32_e32 v93, 0, v93
	v_max_f32_e32 v92, 0, v92
	v_max_f32_e32 v95, 0, v95
	v_max_f32_e32 v94, 0, v94
	v_max_f32_e32 v89, 0, v89
	v_max_f32_e32 v88, 0, v88
	v_max_f32_e32 v91, 0, v91
	v_max_f32_e32 v90, 0, v90
	v_pk_mul_f32 v[94:95], v[94:95], v[94:95]
	v_pk_mul_f32 v[92:93], v[92:93], v[92:93]
	v_pk_mul_f32 v[90:91], v[90:91], v[90:91]
	v_pk_mul_f32 v[88:89], v[88:89], v[88:89]
.LBB0_688:
	v_or_b32_e32 v96, 32, v112
	v_mul_lo_u32 v98, s7, v96
	v_mad_u64_u32 v[96:97], s[20:21], s6, v96, 0
	v_add3_u32 v97, v97, v150, v98
	v_lshl_add_u64 v[96:97], v[96:97], 1, s[24:25]
	v_lshl_add_u64 v[96:97], v[114:115], 1, v[96:97]
	v_cvt_pk_bf16_f32 v92, v92, v93
	v_cvt_pk_bf16_f32 v93, v94, v95
	v_cvt_pk_bf16_f32 v94, v88, v89
	v_cvt_pk_bf16_f32 v95, v90, v91
	s_and_b64 vcc, exec, s[38:39]
	global_store_dwordx4 v[96:97], v[92:95], off
	s_cbranch_vccnz .LBB0_690
	v_max_f32_e32 v85, 0, v85
	v_max_f32_e32 v84, 0, v84
	v_max_f32_e32 v87, 0, v87
	v_max_f32_e32 v86, 0, v86
	v_max_f32_e32 v81, 0, v81
	v_max_f32_e32 v80, 0, v80
	v_max_f32_e32 v83, 0, v83
	v_max_f32_e32 v82, 0, v82
	v_pk_mul_f32 v[86:87], v[86:87], v[86:87]
	v_pk_mul_f32 v[84:85], v[84:85], v[84:85]
	v_pk_mul_f32 v[82:83], v[82:83], v[82:83]
	v_pk_mul_f32 v[80:81], v[80:81], v[80:81]
.LBB0_690:
	v_cvt_pk_bf16_f32 v84, v84, v85
	v_cvt_pk_bf16_f32 v85, v86, v87
	v_cvt_pk_bf16_f32 v86, v80, v81
	v_cvt_pk_bf16_f32 v87, v82, v83
	s_and_b64 vcc, exec, s[38:39]
	global_store_dwordx4 v[96:97], v[84:87], off offset:256
	s_cbranch_vccnz .LBB0_692
	v_max_f32_e32 v77, 0, v77
	v_max_f32_e32 v76, 0, v76
	v_max_f32_e32 v79, 0, v79
	v_max_f32_e32 v78, 0, v78
	v_max_f32_e32 v73, 0, v73
	v_max_f32_e32 v72, 0, v72
	v_max_f32_e32 v75, 0, v75
	v_max_f32_e32 v74, 0, v74
	v_pk_mul_f32 v[78:79], v[78:79], v[78:79]
	v_pk_mul_f32 v[76:77], v[76:77], v[76:77]
	v_pk_mul_f32 v[74:75], v[74:75], v[74:75]
	v_pk_mul_f32 v[72:73], v[72:73], v[72:73]
.LBB0_692:
	v_or_b32_e32 v80, 48, v112
	v_mul_lo_u32 v82, s7, v80
	v_mad_u64_u32 v[80:81], s[20:21], s6, v80, 0
	v_add3_u32 v81, v81, v150, v82
	v_lshl_add_u64 v[80:81], v[80:81], 1, s[24:25]
	v_lshl_add_u64 v[80:81], v[114:115], 1, v[80:81]
	v_cvt_pk_bf16_f32 v76, v76, v77
	v_cvt_pk_bf16_f32 v77, v78, v79
	v_cvt_pk_bf16_f32 v78, v72, v73
	v_cvt_pk_bf16_f32 v79, v74, v75
	s_and_b64 vcc, exec, s[38:39]
	global_store_dwordx4 v[80:81], v[76:79], off
	s_cbranch_vccnz .LBB0_694
	v_max_f32_e32 v69, 0, v69
	v_max_f32_e32 v68, 0, v68
	v_max_f32_e32 v71, 0, v71
	v_max_f32_e32 v70, 0, v70
	v_max_f32_e32 v65, 0, v65
	v_max_f32_e32 v64, 0, v64
	v_max_f32_e32 v67, 0, v67
	v_max_f32_e32 v66, 0, v66
	v_pk_mul_f32 v[70:71], v[70:71], v[70:71]
	v_pk_mul_f32 v[68:69], v[68:69], v[68:69]
	v_pk_mul_f32 v[66:67], v[66:67], v[66:67]
	v_pk_mul_f32 v[64:65], v[64:65], v[64:65]
.LBB0_694:
	v_cvt_pk_bf16_f32 v68, v68, v69
	v_cvt_pk_bf16_f32 v69, v70, v71
	v_cvt_pk_bf16_f32 v70, v64, v65
	v_cvt_pk_bf16_f32 v71, v66, v67
	s_and_b64 vcc, exec, s[38:39]
	global_store_dwordx4 v[80:81], v[68:71], off offset:256
	s_cbranch_vccnz .LBB0_696
	v_max_f32_e32 v61, 0, v61
	v_max_f32_e32 v60, 0, v60
	v_max_f32_e32 v63, 0, v63
	v_max_f32_e32 v62, 0, v62
	v_max_f32_e32 v57, 0, v57
	v_max_f32_e32 v56, 0, v56
	v_max_f32_e32 v59, 0, v59
	v_max_f32_e32 v58, 0, v58
	v_pk_mul_f32 v[62:63], v[62:63], v[62:63]
	v_pk_mul_f32 v[60:61], v[60:61], v[60:61]
	v_pk_mul_f32 v[58:59], v[58:59], v[58:59]
	v_pk_mul_f32 v[56:57], v[56:57], v[56:57]
.LBB0_696:
	v_add_u32_e32 v64, 0x80, v112
	v_ashrrev_i32_e32 v65, 31, v64
	v_mul_lo_u32 v66, s6, v65
	v_mul_lo_u32 v67, s7, v64
	v_mad_u64_u32 v[64:65], s[20:21], s6, v64, 0
	v_add3_u32 v65, v65, v66, v67
	v_lshl_add_u64 v[64:65], v[64:65], 1, s[24:25]
	v_lshl_add_u64 v[64:65], v[114:115], 1, v[64:65]
	v_cvt_pk_bf16_f32 v60, v60, v61
	v_cvt_pk_bf16_f32 v61, v62, v63
	v_cvt_pk_bf16_f32 v62, v56, v57
	v_cvt_pk_bf16_f32 v63, v58, v59
	s_and_b64 vcc, exec, s[38:39]
	global_store_dwordx4 v[64:65], v[60:63], off
	s_cbranch_vccnz .LBB0_698
	v_max_f32_e32 v53, 0, v53
	v_max_f32_e32 v52, 0, v52
	v_max_f32_e32 v55, 0, v55
	v_max_f32_e32 v54, 0, v54
	v_max_f32_e32 v49, 0, v49
	v_max_f32_e32 v48, 0, v48
	v_max_f32_e32 v51, 0, v51
	v_max_f32_e32 v50, 0, v50
	v_pk_mul_f32 v[54:55], v[54:55], v[54:55]
	v_pk_mul_f32 v[52:53], v[52:53], v[52:53]
	v_pk_mul_f32 v[50:51], v[50:51], v[50:51]
	v_pk_mul_f32 v[48:49], v[48:49], v[48:49]
.LBB0_698:
	v_cvt_pk_bf16_f32 v52, v52, v53
	v_cvt_pk_bf16_f32 v53, v54, v55
	v_cvt_pk_bf16_f32 v54, v48, v49
	v_cvt_pk_bf16_f32 v55, v50, v51
	s_and_b64 vcc, exec, s[38:39]
	global_store_dwordx4 v[64:65], v[52:55], off offset:256
	s_cbranch_vccnz .LBB0_700
	v_max_f32_e32 v45, 0, v45
	v_max_f32_e32 v44, 0, v44
	v_max_f32_e32 v47, 0, v47
	v_max_f32_e32 v46, 0, v46
	v_max_f32_e32 v41, 0, v41
	v_max_f32_e32 v40, 0, v40
	v_max_f32_e32 v43, 0, v43
	v_max_f32_e32 v42, 0, v42
	v_pk_mul_f32 v[46:47], v[46:47], v[46:47]
	v_pk_mul_f32 v[44:45], v[44:45], v[44:45]
	v_pk_mul_f32 v[42:43], v[42:43], v[42:43]
	v_pk_mul_f32 v[40:41], v[40:41], v[40:41]
.LBB0_700:
	v_add_u32_e32 v48, 0x90, v112
	v_ashrrev_i32_e32 v49, 31, v48
	v_mul_lo_u32 v50, s6, v49
	v_mul_lo_u32 v51, s7, v48
	v_mad_u64_u32 v[48:49], s[20:21], s6, v48, 0
	v_add3_u32 v49, v49, v50, v51
	v_lshl_add_u64 v[48:49], v[48:49], 1, s[24:25]
	v_lshl_add_u64 v[48:49], v[114:115], 1, v[48:49]
	v_cvt_pk_bf16_f32 v44, v44, v45
	v_cvt_pk_bf16_f32 v45, v46, v47
	v_cvt_pk_bf16_f32 v46, v40, v41
	v_cvt_pk_bf16_f32 v47, v42, v43
	s_and_b64 vcc, exec, s[38:39]
	global_store_dwordx4 v[48:49], v[44:47], off
	s_cbranch_vccnz .LBB0_702
	v_max_f32_e32 v37, 0, v37
	v_max_f32_e32 v36, 0, v36
	v_max_f32_e32 v39, 0, v39
	v_max_f32_e32 v38, 0, v38
	v_max_f32_e32 v33, 0, v33
	v_max_f32_e32 v32, 0, v32
	v_max_f32_e32 v35, 0, v35
	v_max_f32_e32 v34, 0, v34
	v_pk_mul_f32 v[38:39], v[38:39], v[38:39]
	v_pk_mul_f32 v[36:37], v[36:37], v[36:37]
	v_pk_mul_f32 v[34:35], v[34:35], v[34:35]
	v_pk_mul_f32 v[32:33], v[32:33], v[32:33]
.LBB0_702:
	v_cvt_pk_bf16_f32 v36, v36, v37
	v_cvt_pk_bf16_f32 v37, v38, v39
	v_cvt_pk_bf16_f32 v38, v32, v33
	v_cvt_pk_bf16_f32 v39, v34, v35
	s_and_b64 vcc, exec, s[38:39]
	global_store_dwordx4 v[48:49], v[36:39], off offset:256
	s_cbranch_vccnz .LBB0_704
	v_max_f32_e32 v29, 0, v29
	v_max_f32_e32 v28, 0, v28
	v_max_f32_e32 v31, 0, v31
	v_max_f32_e32 v30, 0, v30
	v_max_f32_e32 v25, 0, v25
	v_max_f32_e32 v24, 0, v24
	v_max_f32_e32 v27, 0, v27
	v_max_f32_e32 v26, 0, v26
	v_pk_mul_f32 v[30:31], v[30:31], v[30:31]
	v_pk_mul_f32 v[28:29], v[28:29], v[28:29]
	v_pk_mul_f32 v[26:27], v[26:27], v[26:27]
	v_pk_mul_f32 v[24:25], v[24:25], v[24:25]
.LBB0_704:
	v_add_u32_e32 v32, 0xa0, v112
	v_ashrrev_i32_e32 v33, 31, v32
	v_mul_lo_u32 v34, s6, v33
	v_mul_lo_u32 v35, s7, v32
	v_mad_u64_u32 v[32:33], s[20:21], s6, v32, 0
	v_add3_u32 v33, v33, v34, v35
	v_lshl_add_u64 v[32:33], v[32:33], 1, s[24:25]
	v_lshl_add_u64 v[32:33], v[114:115], 1, v[32:33]
	v_cvt_pk_bf16_f32 v28, v28, v29
	v_cvt_pk_bf16_f32 v29, v30, v31
	v_cvt_pk_bf16_f32 v30, v24, v25
	v_cvt_pk_bf16_f32 v31, v26, v27
	s_and_b64 vcc, exec, s[38:39]
	global_store_dwordx4 v[32:33], v[28:31], off
	s_cbranch_vccnz .LBB0_706
	v_max_f32_e32 v21, 0, v21
	v_max_f32_e32 v20, 0, v20
	v_max_f32_e32 v23, 0, v23
	v_max_f32_e32 v22, 0, v22
	v_max_f32_e32 v17, 0, v17
	v_max_f32_e32 v16, 0, v16
	v_max_f32_e32 v19, 0, v19
	v_max_f32_e32 v18, 0, v18
	v_pk_mul_f32 v[22:23], v[22:23], v[22:23]
	v_pk_mul_f32 v[20:21], v[20:21], v[20:21]
	v_pk_mul_f32 v[18:19], v[18:19], v[18:19]
	v_pk_mul_f32 v[16:17], v[16:17], v[16:17]
.LBB0_706:
	v_cvt_pk_bf16_f32 v20, v20, v21
	v_cvt_pk_bf16_f32 v21, v22, v23
	v_cvt_pk_bf16_f32 v22, v16, v17
	v_cvt_pk_bf16_f32 v23, v18, v19
	s_and_b64 vcc, exec, s[38:39]
	global_store_dwordx4 v[32:33], v[20:23], off offset:256
	s_cbranch_vccnz .LBB0_708
	v_max_f32_e32 v13, 0, v13
	v_max_f32_e32 v12, 0, v12
	v_max_f32_e32 v15, 0, v15
	v_max_f32_e32 v14, 0, v14
	v_max_f32_e32 v9, 0, v9
	v_max_f32_e32 v8, 0, v8
	v_max_f32_e32 v11, 0, v11
	v_max_f32_e32 v10, 0, v10
	v_pk_mul_f32 v[14:15], v[14:15], v[14:15]
	v_pk_mul_f32 v[12:13], v[12:13], v[12:13]
	v_pk_mul_f32 v[10:11], v[10:11], v[10:11]
	v_pk_mul_f32 v[8:9], v[8:9], v[8:9]
.LBB0_708:
	v_add_u32_e32 v16, 0xb0, v112
	v_ashrrev_i32_e32 v17, 31, v16
	v_mul_lo_u32 v18, s6, v17
	v_mul_lo_u32 v19, s7, v16
	v_mad_u64_u32 v[16:17], s[20:21], s6, v16, 0
	v_add3_u32 v17, v17, v18, v19
	v_lshl_add_u64 v[16:17], v[16:17], 1, s[24:25]
	v_lshl_add_u64 v[16:17], v[114:115], 1, v[16:17]
	v_cvt_pk_bf16_f32 v12, v12, v13
	v_cvt_pk_bf16_f32 v13, v14, v15
	v_cvt_pk_bf16_f32 v14, v8, v9
	v_cvt_pk_bf16_f32 v15, v10, v11
	s_and_b64 vcc, exec, s[38:39]
	global_store_dwordx4 v[16:17], v[12:15], off
	s_cbranch_vccnz .LBB0_710
	v_max_f32_e32 v5, 0, v5
	v_max_f32_e32 v4, 0, v4
	v_max_f32_e32 v7, 0, v7
	v_max_f32_e32 v6, 0, v6
	v_max_f32_e32 v1, 0, v1
	v_max_f32_e32 v0, 0, v0
	v_max_f32_e32 v3, 0, v3
	v_max_f32_e32 v2, 0, v2
	v_pk_mul_f32 v[6:7], v[6:7], v[6:7]
	v_pk_mul_f32 v[4:5], v[4:5], v[4:5]
	v_pk_mul_f32 v[2:3], v[2:3], v[2:3]
	v_pk_mul_f32 v[0:1], v[0:1], v[0:1]
